# cache-policy: nt (streaming) hint on the bf16 epilogue stores of the three big-N GEMMs (P1, P1b, FFN-up): outputs are consumed after the next grid sync by other CUs
# speedup vs baseline: 1.0133x; 1.0065x over previous
; __device__ __forceinline__ unsigned cvt_pk_bf16(float lo, float hi) { unsigned r; asm volatile("v_cvt_pk_bf16_f32 %0, %1, %2" : "=v"(r) : "v"(lo), "v"(hi)); return r; }
;     __device__ __forceinline__ void operator()(f32x4 (&acc)[2][2][4][2], const Unit& u, int wr, int wc, int fr, int fq) const {
;     ...
;         const float sc = (colt < scale_cols) ? QSCALE : 1.f;
;         const bool hi = (fr & 8) != 0;
;         const int colA = col0 + (hi ? 32 : 0);
;         const int rbase = u.pm * BM + wr * 64 + (fr & 7);
; #pragma unroll
;         for (int ai = 0; ai < 2; ++ai)
; #pragma unroll
;             for (int m = 0; m < 4; ++m) {
;                 u32x4 w[2];
; #pragma unroll
;                 for (int bj = 0; bj < 2; ++bj) { f32x4 v0 = acc[ai][bj][m][0], v1 = acc[ai][bj][m][1];
;                     if (act == 1) {
; #pragma unroll
;                         for (int e = 0; e < 4; ++e) { float a = fmaxf(v0[e], 0.f), b = fmaxf(v1[e], 0.f); v0[e] = a * a; v1[e] = b * b; } }
;                     v0 = v0 * sc; v1 = v1 * sc; w[bj].x = cvt_pk_bf16(v0[0], v0[1]); w[bj].y = cvt_pk_bf16(v0[2], v0[3]); w[bj].z = cvt_pk_bf16(v1[0], v1[1]); w[bj].w = cvt_pk_bf16(v1[2], v1[3]); }
;                 const u32x4 snd = hi ? w[0] : w[1]; u32x4 rcv;
;                 rcv.x = (unsigned)__builtin_amdgcn_update_dpp(0, (int)snd.x, 0x128, 0xF, 0xF, false); rcv.y = (unsigned)__builtin_amdgcn_update_dpp(0, (int)snd.y, 0x128, 0xF, 0xF, false);
;                 rcv.z = (unsigned)__builtin_amdgcn_update_dpp(0, (int)snd.z, 0x128, 0xF, 0xF, false); rcv.w = (unsigned)__builtin_amdgcn_update_dpp(0, (int)snd.w, 0x128, 0xF, 0xF, false);
;                 const u32x4 o1 = hi ? rcv : w[0], o2 = hi ? w[1] : rcv;
;                 const int r1 = rbase + ai * HALF + m * 16;
;                 bf16_t* p1 = O + (size_t)(r1 & rowmask) * ldc + colA; bf16_t* p2 = O + (size_t)((r1 + 8) & rowmask) * ldc + colA;
;                 if (O) { *(u32x4*)p1 = o1; *(u32x4*)p2 = o2; } else asm volatile("" :: "v"(o1), "v"(o2));
.LBB0_151:
	s_add_i32 s2, s11, s35
	s_cmpk_lt_i32 s11, 0x200
	s_cselect_b64 vcc, -1, 0
	v_cndmask_b32_e32 v0, 1.0, v245, vcc
	v_and_b32_e32 v131, 8, v152
	v_cmp_eq_u32_e32 vcc, 0, v131
	v_pk_mul_f32 v[128:129], v[0:1], v[128:129] op_sel_hi:[0,1]
	v_pk_mul_f32 v[126:127], v[0:1], v[126:127] op_sel_hi:[0,1]
	v_pk_mul_f32 v[124:125], v[0:1], v[124:125] op_sel_hi:[0,1]
	v_pk_mul_f32 v[122:123], v[0:1], v[122:123] op_sel_hi:[0,1]
	v_pk_mul_f32 v[116:117], v[116:117], v[0:1] op_sel_hi:[1,0]
	v_pk_mul_f32 v[114:115], v[114:115], v[0:1] op_sel_hi:[1,0]
	v_lshlrev_b32_e32 v130, 3, v153
	v_lshlrev_b32_e32 v131, 2, v131
	v_cvt_pk_bf16_f32 v126, v126, v127
	v_cvt_pk_bf16_f32 v127, v128, v129
	v_cvt_pk_bf16_f32 v122, v122, v123
	v_cvt_pk_bf16_f32 v123, v124, v125
	v_pk_mul_f32 v[120:121], v[120:121], v[0:1] op_sel_hi:[1,0]
	v_pk_mul_f32 v[118:119], v[118:119], v[0:1] op_sel_hi:[1,0]
	v_mov_b32_e32 v129, v1
	v_cvt_pk_bf16_f32 v124, v118, v119
	v_cvt_pk_bf16_f32 v125, v120, v121
	v_cvt_pk_bf16_f32 v114, v114, v115
	v_cvt_pk_bf16_f32 v115, v116, v117
	v_add3_u32 v132, s2, v130, v131
	v_cndmask_b32_e32 v117, v127, v125, vcc
	v_and_or_b32 v130, v152, 7, s30
	v_cndmask_b32_e32 v116, v123, v115, vcc
	v_cndmask_b32_e32 v118, v122, v114, vcc
	v_cndmask_b32_e32 v119, v126, v124, vcc
	v_mov_b32_e32 v128, v1
	v_mov_b32_dpp v129, v117 row_ror:8 row_mask:0xf bank_mask:0xf
	v_mov_b32_e32 v117, v1
	v_mov_b32_e32 v131, v1
	v_add_u32_e32 v130, s13, v130
	v_mov_b32_dpp v128, v119 row_ror:8 row_mask:0xf bank_mask:0xf
	v_mov_b32_dpp v117, v118 row_ror:8 row_mask:0xf bank_mask:0xf
	v_mov_b32_dpp v131, v116 row_ror:8 row_mask:0xf bank_mask:0xf
	v_ashrrev_i32_e32 v133, 31, v132
	v_cndmask_b32_e32 v121, v131, v123, vcc
	v_cndmask_b32_e32 v120, v117, v122, vcc
	v_cndmask_b32_e32 v123, v125, v129, vcc
	v_cndmask_b32_e32 v125, v115, v131, vcc
	v_cndmask_b32_e32 v122, v124, v128, vcc
	v_cndmask_b32_e32 v124, v114, v117, vcc
	v_or_b32_e32 v116, 8, v130
	v_mov_b64_e32 v[114:115], s[84:85]
	s_movk_i32 s4, 0x1c00
	v_cndmask_b32_e32 v119, v129, v127, vcc
	v_cndmask_b32_e32 v118, v128, v126, vcc
	v_mad_i64_i32 v[126:127], s[2:3], v116, s4, v[114:115]
	v_lshlrev_b64 v[116:117], 1, v[132:133]
	v_mad_i64_i32 v[128:129], s[2:3], v130, s4, v[114:115]
	v_lshl_add_u64 v[128:129], v[128:129], 0, v[116:117]
	v_pk_mul_f32 v[110:111], v[0:1], v[110:111] op_sel_hi:[0,1]
	v_pk_mul_f32 v[108:109], v[0:1], v[108:109] op_sel_hi:[0,1]
	v_pk_mul_f32 v[106:107], v[0:1], v[106:107] op_sel_hi:[0,1]
	v_pk_mul_f32 v[104:105], v[104:105], v[0:1] op_sel_hi:[1,0]
	v_pk_mul_f32 v[102:103], v[102:103], v[0:1] op_sel_hi:[1,0]
	v_pk_mul_f32 v[100:101], v[100:101], v[0:1] op_sel_hi:[1,0]
	v_lshl_add_u64 v[126:127], v[126:127], 0, v[116:117]
	global_store_dwordx4 v[128:129], v[118:121], off nt
	global_store_dwordx4 v[126:127], v[122:125], off nt
	v_pk_mul_f32 v[112:113], v[0:1], v[112:113] op_sel_hi:[0,1]
	v_cvt_pk_bf16_f32 v110, v110, v111
	v_cvt_pk_bf16_f32 v111, v112, v113
	v_cvt_pk_bf16_f32 v106, v106, v107
	v_cvt_pk_bf16_f32 v107, v108, v109
	v_pk_mul_f32 v[98:99], v[98:99], v[0:1] op_sel_hi:[1,0]
	v_cvt_pk_bf16_f32 v102, v102, v103
	v_cvt_pk_bf16_f32 v103, v104, v105
	v_mov_b32_e32 v108, v1
	v_cvt_pk_bf16_f32 v104, v98, v99
	v_cvt_pk_bf16_f32 v105, v100, v101
	v_cndmask_b32_e32 v101, v110, v102, vcc
	v_cndmask_b32_e32 v98, v107, v105, vcc
	v_cndmask_b32_e32 v99, v111, v103, vcc
	v_cndmask_b32_e32 v100, v106, v104, vcc
	v_mov_b32_dpp v108, v101 row_ror:8 row_mask:0xf bank_mask:0xf
	v_mov_b32_e32 v109, v1
	v_mov_b32_e32 v112, v1
	v_mov_b32_e32 v113, v1
	v_mov_b32_dpp v109, v99 row_ror:8 row_mask:0xf bank_mask:0xf
	v_mov_b32_dpp v112, v100 row_ror:8 row_mask:0xf bank_mask:0xf
	v_mov_b32_dpp v113, v98 row_ror:8 row_mask:0xf bank_mask:0xf
	v_cndmask_b32_e32 v98, v108, v110, vcc
	v_cndmask_b32_e32 v102, v102, v108, vcc
	v_or_b32_e32 v108, 16, v130
	v_cndmask_b32_e32 v99, v109, v111, vcc
	v_cndmask_b32_e32 v100, v112, v106, vcc
	v_cndmask_b32_e32 v103, v103, v109, vcc
	v_or_b32_e32 v106, 24, v130
	v_mad_i64_i32 v[108:109], s[2:3], v108, s4, v[114:115]
	v_cndmask_b32_e32 v101, v113, v107, vcc
	v_mad_i64_i32 v[106:107], s[2:3], v106, s4, v[114:115]
	v_lshl_add_u64 v[108:109], v[108:109], 0, v[116:117]
	v_pk_mul_f32 v[94:95], v[0:1], v[94:95] op_sel_hi:[0,1]
	v_pk_mul_f32 v[92:93], v[0:1], v[92:93] op_sel_hi:[0,1]
	v_pk_mul_f32 v[90:91], v[0:1], v[90:91] op_sel_hi:[0,1]
	v_pk_mul_f32 v[88:89], v[88:89], v[0:1] op_sel_hi:[1,0]
	v_pk_mul_f32 v[86:87], v[86:87], v[0:1] op_sel_hi:[1,0]
	v_pk_mul_f32 v[84:85], v[84:85], v[0:1] op_sel_hi:[1,0]
	v_cndmask_b32_e32 v105, v105, v113, vcc
	v_cndmask_b32_e32 v104, v104, v112, vcc
	v_lshl_add_u64 v[106:107], v[106:107], 0, v[116:117]
	global_store_dwordx4 v[108:109], v[98:101], off nt
	global_store_dwordx4 v[106:107], v[102:105], off nt
	v_pk_mul_f32 v[96:97], v[0:1], v[96:97] op_sel_hi:[0,1]
	v_cvt_pk_bf16_f32 v94, v94, v95
	v_cvt_pk_bf16_f32 v95, v96, v97
	v_cvt_pk_bf16_f32 v90, v90, v91
	v_cvt_pk_bf16_f32 v91, v92, v93
	v_pk_mul_f32 v[82:83], v[82:83], v[0:1] op_sel_hi:[1,0]
	v_cvt_pk_bf16_f32 v86, v86, v87
	v_cvt_pk_bf16_f32 v87, v88, v89
	v_mov_b32_e32 v92, v1
	v_cvt_pk_bf16_f32 v88, v82, v83
	v_cvt_pk_bf16_f32 v89, v84, v85
	v_cndmask_b32_e32 v85, v94, v86, vcc
	v_cndmask_b32_e32 v82, v91, v89, vcc
	v_cndmask_b32_e32 v83, v95, v87, vcc
	v_cndmask_b32_e32 v84, v90, v88, vcc
	v_mov_b32_dpp v92, v85 row_ror:8 row_mask:0xf bank_mask:0xf
	v_mov_b32_e32 v93, v1
	v_mov_b32_e32 v96, v1
	v_mov_b32_e32 v97, v1
	v_mov_b32_dpp v93, v83 row_ror:8 row_mask:0xf bank_mask:0xf
	v_mov_b32_dpp v96, v84 row_ror:8 row_mask:0xf bank_mask:0xf
	v_mov_b32_dpp v97, v82 row_ror:8 row_mask:0xf bank_mask:0xf
; __device__ __forceinline__ unsigned cvt_pk_bf16(float lo, float hi) { unsigned r; asm volatile("v_cvt_pk_bf16_f32 %0, %1, %2" : "=v"(r) : "v"(lo), "v"(hi)); return r; }
;     __device__ __forceinline__ void operator()(f32x4 (&acc)[2][2][4][2], const Unit& u, int wr, int wc, int fr, int fq) const {
;     ...
;         for (int ai = 0; ai < 2; ++ai)
; #pragma unroll
;             for (int m = 0; m < 4; ++m) {
;                 u32x4 w[2];
; #pragma unroll
;                 for (int bj = 0; bj < 2; ++bj) { f32x4 v0 = acc[ai][bj][m][0], v1 = acc[ai][bj][m][1];
;                     if (act == 1) {
; #pragma unroll
;                         for (int e = 0; e < 4; ++e) { float a = fmaxf(v0[e], 0.f), b = fmaxf(v1[e], 0.f); v0[e] = a * a; v1[e] = b * b; } }
;                     v0 = v0 * sc; v1 = v1 * sc; w[bj].x = cvt_pk_bf16(v0[0], v0[1]); w[bj].y = cvt_pk_bf16(v0[2], v0[3]); w[bj].z = cvt_pk_bf16(v1[0], v1[1]); w[bj].w = cvt_pk_bf16(v1[2], v1[3]); }
;                 const u32x4 snd = hi ? w[0] : w[1]; u32x4 rcv;
;                 rcv.x = (unsigned)__builtin_amdgcn_update_dpp(0, (int)snd.x, 0x128, 0xF, 0xF, false); rcv.y = (unsigned)__builtin_amdgcn_update_dpp(0, (int)snd.y, 0x128, 0xF, 0xF, false);
;                 rcv.z = (unsigned)__builtin_amdgcn_update_dpp(0, (int)snd.z, 0x128, 0xF, 0xF, false); rcv.w = (unsigned)__builtin_amdgcn_update_dpp(0, (int)snd.w, 0x128, 0xF, 0xF, false);
;                 const u32x4 o1 = hi ? rcv : w[0], o2 = hi ? w[1] : rcv;
;                 const int r1 = rbase + ai * HALF + m * 16;
;                 bf16_t* p1 = O + (size_t)(r1 & rowmask) * ldc + colA; bf16_t* p2 = O + (size_t)((r1 + 8) & rowmask) * ldc + colA;
;                 if (O) { *(u32x4*)p1 = o1; *(u32x4*)p2 = o2; } else asm volatile("" :: "v"(o1), "v"(o2));
	v_cndmask_b32_e32 v82, v92, v94, vcc
	v_cndmask_b32_e32 v86, v86, v92, vcc
	v_or_b32_e32 v92, 32, v130
	v_cndmask_b32_e32 v83, v93, v95, vcc
	v_cndmask_b32_e32 v84, v96, v90, vcc
	v_cndmask_b32_e32 v87, v87, v93, vcc
	v_or_b32_e32 v90, 40, v130
	v_mad_i64_i32 v[92:93], s[2:3], v92, s4, v[114:115]
	v_cndmask_b32_e32 v85, v97, v91, vcc
	v_mad_i64_i32 v[90:91], s[2:3], v90, s4, v[114:115]
	v_lshl_add_u64 v[92:93], v[92:93], 0, v[116:117]
	v_pk_mul_f32 v[78:79], v[0:1], v[78:79] op_sel_hi:[0,1]
	v_pk_mul_f32 v[76:77], v[0:1], v[76:77] op_sel_hi:[0,1]
	v_pk_mul_f32 v[74:75], v[0:1], v[74:75] op_sel_hi:[0,1]
	v_pk_mul_f32 v[72:73], v[72:73], v[0:1] op_sel_hi:[1,0]
	v_pk_mul_f32 v[70:71], v[70:71], v[0:1] op_sel_hi:[1,0]
	v_pk_mul_f32 v[68:69], v[68:69], v[0:1] op_sel_hi:[1,0]
	v_cndmask_b32_e32 v89, v89, v97, vcc
	v_cndmask_b32_e32 v88, v88, v96, vcc
	v_lshl_add_u64 v[90:91], v[90:91], 0, v[116:117]
	global_store_dwordx4 v[92:93], v[82:85], off nt
	global_store_dwordx4 v[90:91], v[86:89], off nt
	v_pk_mul_f32 v[80:81], v[0:1], v[80:81] op_sel_hi:[0,1]
	v_cvt_pk_bf16_f32 v78, v78, v79
	v_cvt_pk_bf16_f32 v79, v80, v81
	v_cvt_pk_bf16_f32 v74, v74, v75
	v_cvt_pk_bf16_f32 v75, v76, v77
	v_pk_mul_f32 v[66:67], v[66:67], v[0:1] op_sel_hi:[1,0]
	v_cvt_pk_bf16_f32 v70, v70, v71
	v_cvt_pk_bf16_f32 v71, v72, v73
	v_mov_b32_e32 v76, v1
	v_cvt_pk_bf16_f32 v72, v66, v67
	v_cvt_pk_bf16_f32 v73, v68, v69
	v_cndmask_b32_e32 v69, v78, v70, vcc
	v_cndmask_b32_e32 v66, v75, v73, vcc
	v_cndmask_b32_e32 v67, v79, v71, vcc
	v_cndmask_b32_e32 v68, v74, v72, vcc
	v_mov_b32_dpp v76, v69 row_ror:8 row_mask:0xf bank_mask:0xf
	v_mov_b32_e32 v77, v1
	v_mov_b32_e32 v80, v1
	v_mov_b32_e32 v81, v1
	v_mov_b32_dpp v77, v67 row_ror:8 row_mask:0xf bank_mask:0xf
	v_mov_b32_dpp v80, v68 row_ror:8 row_mask:0xf bank_mask:0xf
	v_mov_b32_dpp v81, v66 row_ror:8 row_mask:0xf bank_mask:0xf
	v_cndmask_b32_e32 v66, v76, v78, vcc
	v_cndmask_b32_e32 v70, v70, v76, vcc
	v_or_b32_e32 v76, 48, v130
	v_cndmask_b32_e32 v67, v77, v79, vcc
	v_cndmask_b32_e32 v68, v80, v74, vcc
	v_cndmask_b32_e32 v71, v71, v77, vcc
	v_or_b32_e32 v74, 56, v130
	v_mad_i64_i32 v[76:77], s[2:3], v76, s4, v[114:115]
	v_cndmask_b32_e32 v69, v81, v75, vcc
	v_mad_i64_i32 v[74:75], s[2:3], v74, s4, v[114:115]
	v_lshl_add_u64 v[76:77], v[76:77], 0, v[116:117]
	v_pk_mul_f32 v[64:65], v[0:1], v[64:65] op_sel_hi:[0,1]
	v_pk_mul_f32 v[62:63], v[0:1], v[62:63] op_sel_hi:[0,1]
	v_pk_mul_f32 v[60:61], v[0:1], v[60:61] op_sel_hi:[0,1]
	v_pk_mul_f32 v[58:59], v[0:1], v[58:59] op_sel_hi:[0,1]
	v_pk_mul_f32 v[56:57], v[56:57], v[0:1] op_sel_hi:[1,0]
	v_pk_mul_f32 v[54:55], v[54:55], v[0:1] op_sel_hi:[1,0]
	v_pk_mul_f32 v[52:53], v[52:53], v[0:1] op_sel_hi:[1,0]
	v_pk_mul_f32 v[50:51], v[50:51], v[0:1] op_sel_hi:[1,0]
	v_cndmask_b32_e32 v73, v73, v81, vcc
	v_cndmask_b32_e32 v72, v72, v80, vcc
	v_lshl_add_u64 v[74:75], v[74:75], 0, v[116:117]
	global_store_dwordx4 v[76:77], v[66:69], off nt
	global_store_dwordx4 v[74:75], v[70:73], off nt
	v_cvt_pk_bf16_f32 v62, v62, v63
	v_cvt_pk_bf16_f32 v63, v64, v65
	v_cvt_pk_bf16_f32 v58, v58, v59
	v_cvt_pk_bf16_f32 v59, v60, v61
	v_cvt_pk_bf16_f32 v54, v54, v55
	v_cvt_pk_bf16_f32 v55, v56, v57
	v_cvt_pk_bf16_f32 v56, v50, v51
	v_cvt_pk_bf16_f32 v57, v52, v53
	v_mov_b32_e32 v60, v1
	v_cndmask_b32_e32 v51, v63, v55, vcc
	v_cndmask_b32_e32 v52, v58, v56, vcc
	v_cndmask_b32_e32 v53, v62, v54, vcc
	v_mov_b32_e32 v61, v1
	v_mov_b32_e32 v64, v1
	v_add_u32_e32 v66, 0x80, v130
	v_cndmask_b32_e32 v50, v59, v57, vcc
	v_mov_b32_dpp v60, v53 row_ror:8 row_mask:0xf bank_mask:0xf
	v_mov_b32_dpp v61, v51 row_ror:8 row_mask:0xf bank_mask:0xf
	v_mov_b32_dpp v64, v52 row_ror:8 row_mask:0xf bank_mask:0xf
	v_mov_b32_e32 v65, v1
	v_cndmask_b32_e32 v51, v61, v63, vcc
	v_cndmask_b32_e32 v52, v64, v58, vcc
	v_mov_b32_dpp v65, v50 row_ror:8 row_mask:0xf bank_mask:0xf
	v_cndmask_b32_e32 v50, v60, v62, vcc
	v_cndmask_b32_e32 v55, v55, v61, vcc
	v_cndmask_b32_e32 v54, v54, v60, vcc
	v_add_u32_e32 v58, 0x88, v130
	v_mad_i64_i32 v[60:61], s[2:3], v66, s4, v[114:115]
	v_cndmask_b32_e32 v53, v65, v59, vcc
	v_mad_i64_i32 v[58:59], s[2:3], v58, s4, v[114:115]
	v_lshl_add_u64 v[60:61], v[60:61], 0, v[116:117]
	v_pk_mul_f32 v[46:47], v[0:1], v[46:47] op_sel_hi:[0,1]
	v_pk_mul_f32 v[44:45], v[0:1], v[44:45] op_sel_hi:[0,1]
	v_pk_mul_f32 v[42:43], v[0:1], v[42:43] op_sel_hi:[0,1]
	v_pk_mul_f32 v[40:41], v[40:41], v[0:1] op_sel_hi:[1,0]
	v_pk_mul_f32 v[38:39], v[38:39], v[0:1] op_sel_hi:[1,0]
	v_pk_mul_f32 v[36:37], v[36:37], v[0:1] op_sel_hi:[1,0]
	v_cndmask_b32_e32 v57, v57, v65, vcc
	v_cndmask_b32_e32 v56, v56, v64, vcc
	v_lshl_add_u64 v[58:59], v[58:59], 0, v[116:117]
	global_store_dwordx4 v[60:61], v[50:53], off nt
	global_store_dwordx4 v[58:59], v[54:57], off nt
	v_pk_mul_f32 v[48:49], v[0:1], v[48:49] op_sel_hi:[0,1]
	v_cvt_pk_bf16_f32 v46, v46, v47
	v_cvt_pk_bf16_f32 v47, v48, v49
	v_cvt_pk_bf16_f32 v42, v42, v43
	v_cvt_pk_bf16_f32 v43, v44, v45
	v_pk_mul_f32 v[34:35], v[34:35], v[0:1] op_sel_hi:[1,0]
	v_cvt_pk_bf16_f32 v38, v38, v39
	v_cvt_pk_bf16_f32 v39, v40, v41
; __device__ __forceinline__ unsigned cvt_pk_bf16(float lo, float hi) { unsigned r; asm volatile("v_cvt_pk_bf16_f32 %0, %1, %2" : "=v"(r) : "v"(lo), "v"(hi)); return r; }
;     __device__ __forceinline__ void operator()(f32x4 (&acc)[2][2][4][2], const Unit& u, int wr, int wc, int fr, int fq) const {
;     ...
;         for (int ai = 0; ai < 2; ++ai)
; #pragma unroll
;             for (int m = 0; m < 4; ++m) {
;                 u32x4 w[2];
; #pragma unroll
;                 for (int bj = 0; bj < 2; ++bj) { f32x4 v0 = acc[ai][bj][m][0], v1 = acc[ai][bj][m][1];
;                     if (act == 1) {
; #pragma unroll
;                         for (int e = 0; e < 4; ++e) { float a = fmaxf(v0[e], 0.f), b = fmaxf(v1[e], 0.f); v0[e] = a * a; v1[e] = b * b; } }
;                     v0 = v0 * sc; v1 = v1 * sc; w[bj].x = cvt_pk_bf16(v0[0], v0[1]); w[bj].y = cvt_pk_bf16(v0[2], v0[3]); w[bj].z = cvt_pk_bf16(v1[0], v1[1]); w[bj].w = cvt_pk_bf16(v1[2], v1[3]); }
;                 const u32x4 snd = hi ? w[0] : w[1]; u32x4 rcv;
;                 rcv.x = (unsigned)__builtin_amdgcn_update_dpp(0, (int)snd.x, 0x128, 0xF, 0xF, false); rcv.y = (unsigned)__builtin_amdgcn_update_dpp(0, (int)snd.y, 0x128, 0xF, 0xF, false);
;                 rcv.z = (unsigned)__builtin_amdgcn_update_dpp(0, (int)snd.z, 0x128, 0xF, 0xF, false); rcv.w = (unsigned)__builtin_amdgcn_update_dpp(0, (int)snd.w, 0x128, 0xF, 0xF, false);
;                 const u32x4 o1 = hi ? rcv : w[0], o2 = hi ? w[1] : rcv;
;                 const int r1 = rbase + ai * HALF + m * 16;
;                 bf16_t* p1 = O + (size_t)(r1 & rowmask) * ldc + colA; bf16_t* p2 = O + (size_t)((r1 + 8) & rowmask) * ldc + colA;
;                 if (O) { *(u32x4*)p1 = o1; *(u32x4*)p2 = o2; } else asm volatile("" :: "v"(o1), "v"(o2));
	v_mov_b32_e32 v44, v1
	v_cvt_pk_bf16_f32 v40, v34, v35
	v_cvt_pk_bf16_f32 v41, v36, v37
	v_cndmask_b32_e32 v37, v46, v38, vcc
	v_cndmask_b32_e32 v34, v43, v41, vcc
	v_cndmask_b32_e32 v35, v47, v39, vcc
	v_cndmask_b32_e32 v36, v42, v40, vcc
	v_mov_b32_dpp v44, v37 row_ror:8 row_mask:0xf bank_mask:0xf
	v_mov_b32_e32 v45, v1
	v_mov_b32_e32 v48, v1
	v_mov_b32_e32 v49, v1
	v_mov_b32_dpp v45, v35 row_ror:8 row_mask:0xf bank_mask:0xf
	v_mov_b32_dpp v48, v36 row_ror:8 row_mask:0xf bank_mask:0xf
	v_mov_b32_dpp v49, v34 row_ror:8 row_mask:0xf bank_mask:0xf
	v_cndmask_b32_e32 v34, v44, v46, vcc
	v_cndmask_b32_e32 v38, v38, v44, vcc
	v_add_u32_e32 v44, 0x90, v130
	v_cndmask_b32_e32 v35, v45, v47, vcc
	v_cndmask_b32_e32 v36, v48, v42, vcc
	v_cndmask_b32_e32 v39, v39, v45, vcc
	v_add_u32_e32 v42, 0x98, v130
	v_mad_i64_i32 v[44:45], s[2:3], v44, s4, v[114:115]
	v_cndmask_b32_e32 v37, v49, v43, vcc
	v_mad_i64_i32 v[42:43], s[2:3], v42, s4, v[114:115]
	v_lshl_add_u64 v[44:45], v[44:45], 0, v[116:117]
	v_pk_mul_f32 v[30:31], v[0:1], v[30:31] op_sel_hi:[0,1]
	v_pk_mul_f32 v[28:29], v[0:1], v[28:29] op_sel_hi:[0,1]
	v_pk_mul_f32 v[26:27], v[0:1], v[26:27] op_sel_hi:[0,1]
	v_pk_mul_f32 v[24:25], v[24:25], v[0:1] op_sel_hi:[1,0]
	v_pk_mul_f32 v[22:23], v[22:23], v[0:1] op_sel_hi:[1,0]
	v_pk_mul_f32 v[20:21], v[20:21], v[0:1] op_sel_hi:[1,0]
	v_cndmask_b32_e32 v41, v41, v49, vcc
	v_cndmask_b32_e32 v40, v40, v48, vcc
	v_lshl_add_u64 v[42:43], v[42:43], 0, v[116:117]
	global_store_dwordx4 v[44:45], v[34:37], off nt
	global_store_dwordx4 v[42:43], v[38:41], off nt
	v_pk_mul_f32 v[32:33], v[0:1], v[32:33] op_sel_hi:[0,1]
	v_cvt_pk_bf16_f32 v30, v30, v31
	v_cvt_pk_bf16_f32 v31, v32, v33
	v_cvt_pk_bf16_f32 v26, v26, v27
	v_cvt_pk_bf16_f32 v27, v28, v29
	v_pk_mul_f32 v[18:19], v[18:19], v[0:1] op_sel_hi:[1,0]
	v_cvt_pk_bf16_f32 v22, v22, v23
	v_cvt_pk_bf16_f32 v23, v24, v25
	v_mov_b32_e32 v28, v1
	v_cvt_pk_bf16_f32 v24, v18, v19
	v_cvt_pk_bf16_f32 v25, v20, v21
	v_cndmask_b32_e32 v21, v30, v22, vcc
	v_cndmask_b32_e32 v18, v27, v25, vcc
	v_cndmask_b32_e32 v19, v31, v23, vcc
	v_cndmask_b32_e32 v20, v26, v24, vcc
	v_mov_b32_dpp v28, v21 row_ror:8 row_mask:0xf bank_mask:0xf
	v_mov_b32_e32 v29, v1
	v_mov_b32_e32 v32, v1
	v_mov_b32_e32 v33, v1
	v_mov_b32_dpp v29, v19 row_ror:8 row_mask:0xf bank_mask:0xf
	v_mov_b32_dpp v32, v20 row_ror:8 row_mask:0xf bank_mask:0xf
	v_mov_b32_dpp v33, v18 row_ror:8 row_mask:0xf bank_mask:0xf
	v_cndmask_b32_e32 v18, v28, v30, vcc
	v_cndmask_b32_e32 v22, v22, v28, vcc
	v_add_u32_e32 v28, 0xa0, v130
	v_cndmask_b32_e32 v19, v29, v31, vcc
	v_cndmask_b32_e32 v20, v32, v26, vcc
	v_cndmask_b32_e32 v23, v23, v29, vcc
	v_add_u32_e32 v26, 0xa8, v130
	v_mad_i64_i32 v[28:29], s[2:3], v28, s4, v[114:115]
	v_cndmask_b32_e32 v21, v33, v27, vcc
	v_mad_i64_i32 v[26:27], s[2:3], v26, s4, v[114:115]
	v_lshl_add_u64 v[28:29], v[28:29], 0, v[116:117]
	v_pk_mul_f32 v[14:15], v[0:1], v[14:15] op_sel_hi:[0,1]
	v_pk_mul_f32 v[12:13], v[0:1], v[12:13] op_sel_hi:[0,1]
	v_pk_mul_f32 v[10:11], v[0:1], v[10:11] op_sel_hi:[0,1]
	v_pk_mul_f32 v[8:9], v[8:9], v[0:1] op_sel_hi:[1,0]
	v_pk_mul_f32 v[6:7], v[6:7], v[0:1] op_sel_hi:[1,0]
	v_pk_mul_f32 v[4:5], v[4:5], v[0:1] op_sel_hi:[1,0]
	v_pk_mul_f32 v[2:3], v[2:3], v[0:1] op_sel_hi:[1,0]
	v_cndmask_b32_e32 v25, v25, v33, vcc
	v_cndmask_b32_e32 v24, v24, v32, vcc
	v_lshl_add_u64 v[26:27], v[26:27], 0, v[116:117]
	global_store_dwordx4 v[28:29], v[18:21], off nt
	global_store_dwordx4 v[26:27], v[22:25], off nt
	v_pk_mul_f32 v[16:17], v[0:1], v[16:17] op_sel_hi:[0,1]
	v_cvt_pk_bf16_f32 v14, v14, v15
	v_cvt_pk_bf16_f32 v15, v16, v17
	v_cvt_pk_bf16_f32 v10, v10, v11
	v_cvt_pk_bf16_f32 v11, v12, v13
	v_cvt_pk_bf16_f32 v0, v6, v7
	v_cvt_pk_bf16_f32 v6, v8, v9
	v_cvt_pk_bf16_f32 v8, v2, v3
	v_cvt_pk_bf16_f32 v9, v4, v5
	v_mov_b32_e32 v12, v1
	v_cndmask_b32_e32 v3, v15, v6, vcc
	v_cndmask_b32_e32 v4, v10, v8, vcc
	v_cndmask_b32_e32 v5, v14, v0, vcc
	v_mov_b32_e32 v7, v1
	v_mov_b32_e32 v13, v1
	v_cndmask_b32_e32 v2, v11, v9, vcc
	v_mov_b32_dpp v12, v5 row_ror:8 row_mask:0xf bank_mask:0xf
	v_mov_b32_dpp v7, v3 row_ror:8 row_mask:0xf bank_mask:0xf
	v_mov_b32_dpp v13, v4 row_ror:8 row_mask:0xf bank_mask:0xf
	v_mov_b32_e32 v16, v1
	v_cndmask_b32_e32 v3, v7, v15, vcc
	v_cndmask_b32_e32 v4, v13, v10, vcc
	v_mov_b32_dpp v16, v2 row_ror:8 row_mask:0xf bank_mask:0xf
	v_cndmask_b32_e32 v7, v6, v7, vcc
	v_cndmask_b32_e32 v6, v0, v12, vcc
	v_add_u32_e32 v0, 0xb0, v130
	v_add_u32_e32 v10, 0xb8, v130
	v_cndmask_b32_e32 v5, v16, v11, vcc
	v_cndmask_b32_e32 v2, v12, v14, vcc
	v_cndmask_b32_e32 v8, v8, v13, vcc
	v_mad_i64_i32 v[10:11], s[2:3], v10, s4, v[114:115]
	v_mad_i64_i32 v[12:13], s[2:3], v0, s4, v[114:115]
	v_cndmask_b32_e32 v9, v9, v16, vcc
	v_lshl_add_u64 v[12:13], v[12:13], 0, v[116:117]
	s_mov_b64 s[2:3], -1
	s_andn2_b64 vcc, exec, s[0:1]
	v_lshl_add_u64 v[10:11], v[10:11], 0, v[116:117]
	global_store_dwordx4 v[12:13], v[2:5], off nt
	global_store_dwordx4 v[10:11], v[6:9], off nt
	s_cbranch_vccnz .LBB0_140
	s_andn2_b64 vcc, exec, s[6:7]
	s_cbranch_vccnz .LBB0_139
	s_barrier
	s_branch .LBB0_139

; __device__ __forceinline__ unsigned cvt_pk_bf16(float lo, float hi) { unsigned r; asm volatile("v_cvt_pk_bf16_f32 %0, %1, %2" : "=v"(r) : "v"(lo), "v"(hi)); return r; }
;     __device__ __forceinline__ void operator()(f32x4 (&acc)[2][2][4][2], const Unit& u, int wr, int wc, int fr, int fq) const {
;     ...
;         const float sc = (colt < scale_cols) ? QSCALE : 1.f;
;         const bool hi = (fr & 8) != 0;
;         const int colA = col0 + (hi ? 32 : 0);
;         const int rbase = u.pm * BM + wr * 64 + (fr & 7);
; #pragma unroll
;         for (int ai = 0; ai < 2; ++ai)
; #pragma unroll
;             for (int m = 0; m < 4; ++m) {
;                 u32x4 w[2];
; #pragma unroll
;                 for (int bj = 0; bj < 2; ++bj) { f32x4 v0 = acc[ai][bj][m][0], v1 = acc[ai][bj][m][1];
;                     if (act == 1) {
; #pragma unroll
;                         for (int e = 0; e < 4; ++e) { float a = fmaxf(v0[e], 0.f), b = fmaxf(v1[e], 0.f); v0[e] = a * a; v1[e] = b * b; } }
;                     v0 = v0 * sc; v1 = v1 * sc; w[bj].x = cvt_pk_bf16(v0[0], v0[1]); w[bj].y = cvt_pk_bf16(v0[2], v0[3]); w[bj].z = cvt_pk_bf16(v1[0], v1[1]); w[bj].w = cvt_pk_bf16(v1[2], v1[3]); }
;                 const u32x4 snd = hi ? w[0] : w[1]; u32x4 rcv;
;                 rcv.x = (unsigned)__builtin_amdgcn_update_dpp(0, (int)snd.x, 0x128, 0xF, 0xF, false); rcv.y = (unsigned)__builtin_amdgcn_update_dpp(0, (int)snd.y, 0x128, 0xF, 0xF, false);
;                 rcv.z = (unsigned)__builtin_amdgcn_update_dpp(0, (int)snd.z, 0x128, 0xF, 0xF, false); rcv.w = (unsigned)__builtin_amdgcn_update_dpp(0, (int)snd.w, 0x128, 0xF, 0xF, false);
;                 const u32x4 o1 = hi ? rcv : w[0], o2 = hi ? w[1] : rcv;
;                 const int r1 = rbase + ai * HALF + m * 16;
;                 bf16_t* p1 = O + (size_t)(r1 & rowmask) * ldc + colA; bf16_t* p2 = O + (size_t)((r1 + 8) & rowmask) * ldc + colA;
;                 if (O) { *(u32x4*)p1 = o1; *(u32x4*)p2 = o2; } else asm volatile("" :: "v"(o1), "v"(o2));
.LBB0_440:
	s_add_i32 s2, s11, s35
	s_cmpk_lt_i32 s11, 0x400
	s_cselect_b64 vcc, -1, 0
	v_cndmask_b32_e32 v0, 1.0, v245, vcc
	v_and_b32_e32 v131, 8, v152
	v_cmp_eq_u32_e32 vcc, 0, v131
	v_pk_mul_f32 v[128:129], v[0:1], v[128:129] op_sel_hi:[0,1]
	v_pk_mul_f32 v[126:127], v[0:1], v[126:127] op_sel_hi:[0,1]
	v_pk_mul_f32 v[124:125], v[0:1], v[124:125] op_sel_hi:[0,1]
	v_pk_mul_f32 v[122:123], v[0:1], v[122:123] op_sel_hi:[0,1]
	v_pk_mul_f32 v[116:117], v[116:117], v[0:1] op_sel_hi:[1,0]
	v_pk_mul_f32 v[114:115], v[114:115], v[0:1] op_sel_hi:[1,0]
	v_lshlrev_b32_e32 v130, 3, v153
	v_lshlrev_b32_e32 v131, 2, v131
	v_cvt_pk_bf16_f32 v126, v126, v127
	v_cvt_pk_bf16_f32 v127, v128, v129
	v_cvt_pk_bf16_f32 v122, v122, v123
	v_cvt_pk_bf16_f32 v123, v124, v125
	v_pk_mul_f32 v[120:121], v[120:121], v[0:1] op_sel_hi:[1,0]
	v_pk_mul_f32 v[118:119], v[118:119], v[0:1] op_sel_hi:[1,0]
	v_mov_b32_e32 v129, v1
	v_cvt_pk_bf16_f32 v124, v118, v119
	v_cvt_pk_bf16_f32 v125, v120, v121
	v_cvt_pk_bf16_f32 v114, v114, v115
	v_cvt_pk_bf16_f32 v115, v116, v117
	v_add3_u32 v132, s2, v130, v131
	v_cndmask_b32_e32 v117, v127, v125, vcc
	v_and_or_b32 v130, v152, 7, s30
	v_cndmask_b32_e32 v116, v123, v115, vcc
	v_cndmask_b32_e32 v118, v122, v114, vcc
	v_cndmask_b32_e32 v119, v126, v124, vcc
	v_mov_b32_e32 v128, v1
	v_mov_b32_dpp v129, v117 row_ror:8 row_mask:0xf bank_mask:0xf
	v_mov_b32_e32 v117, v1
	v_mov_b32_e32 v131, v1
	v_add_u32_e32 v130, s13, v130
	v_mov_b32_dpp v128, v119 row_ror:8 row_mask:0xf bank_mask:0xf
	v_mov_b32_dpp v117, v118 row_ror:8 row_mask:0xf bank_mask:0xf
	v_mov_b32_dpp v131, v116 row_ror:8 row_mask:0xf bank_mask:0xf
	v_ashrrev_i32_e32 v133, 31, v132
	v_cndmask_b32_e32 v121, v131, v123, vcc
	v_cndmask_b32_e32 v120, v117, v122, vcc
	v_cndmask_b32_e32 v123, v125, v129, vcc
	v_cndmask_b32_e32 v125, v115, v131, vcc
	v_cndmask_b32_e32 v122, v124, v128, vcc
	v_cndmask_b32_e32 v124, v114, v117, vcc
	v_or_b32_e32 v116, 8, v130
	v_mov_b64_e32 v[114:115], s[84:85]
	s_movk_i32 s4, 0x1800
	v_cndmask_b32_e32 v119, v129, v127, vcc
	v_cndmask_b32_e32 v118, v128, v126, vcc
	v_mad_i64_i32 v[126:127], s[2:3], v116, s4, v[114:115]
	v_lshlrev_b64 v[116:117], 1, v[132:133]
	v_mad_i64_i32 v[128:129], s[2:3], v130, s4, v[114:115]
	v_lshl_add_u64 v[128:129], v[128:129], 0, v[116:117]
	v_pk_mul_f32 v[110:111], v[0:1], v[110:111] op_sel_hi:[0,1]
	v_pk_mul_f32 v[108:109], v[0:1], v[108:109] op_sel_hi:[0,1]
	v_pk_mul_f32 v[106:107], v[0:1], v[106:107] op_sel_hi:[0,1]
	v_pk_mul_f32 v[104:105], v[104:105], v[0:1] op_sel_hi:[1,0]
	v_pk_mul_f32 v[102:103], v[102:103], v[0:1] op_sel_hi:[1,0]
	v_pk_mul_f32 v[100:101], v[100:101], v[0:1] op_sel_hi:[1,0]
	v_lshl_add_u64 v[126:127], v[126:127], 0, v[116:117]
	global_store_dwordx4 v[128:129], v[118:121], off nt
	global_store_dwordx4 v[126:127], v[122:125], off nt
	v_pk_mul_f32 v[112:113], v[0:1], v[112:113] op_sel_hi:[0,1]
	v_cvt_pk_bf16_f32 v110, v110, v111
	v_cvt_pk_bf16_f32 v111, v112, v113
	v_cvt_pk_bf16_f32 v106, v106, v107
	v_cvt_pk_bf16_f32 v107, v108, v109
	v_pk_mul_f32 v[98:99], v[98:99], v[0:1] op_sel_hi:[1,0]
	v_cvt_pk_bf16_f32 v102, v102, v103
	v_cvt_pk_bf16_f32 v103, v104, v105
	v_mov_b32_e32 v108, v1
	v_cvt_pk_bf16_f32 v104, v98, v99
	v_cvt_pk_bf16_f32 v105, v100, v101
	v_cndmask_b32_e32 v101, v110, v102, vcc
	v_cndmask_b32_e32 v98, v107, v105, vcc
	v_cndmask_b32_e32 v99, v111, v103, vcc
	v_cndmask_b32_e32 v100, v106, v104, vcc
	v_mov_b32_dpp v108, v101 row_ror:8 row_mask:0xf bank_mask:0xf
	v_mov_b32_e32 v109, v1
	v_mov_b32_e32 v112, v1
	v_mov_b32_e32 v113, v1
	v_mov_b32_dpp v109, v99 row_ror:8 row_mask:0xf bank_mask:0xf
	v_mov_b32_dpp v112, v100 row_ror:8 row_mask:0xf bank_mask:0xf
	v_mov_b32_dpp v113, v98 row_ror:8 row_mask:0xf bank_mask:0xf
	v_cndmask_b32_e32 v98, v108, v110, vcc
	v_cndmask_b32_e32 v102, v102, v108, vcc
	v_or_b32_e32 v108, 16, v130
	v_cndmask_b32_e32 v99, v109, v111, vcc
	v_cndmask_b32_e32 v100, v112, v106, vcc
	v_cndmask_b32_e32 v103, v103, v109, vcc
	v_or_b32_e32 v106, 24, v130
	v_mad_i64_i32 v[108:109], s[2:3], v108, s4, v[114:115]
	v_cndmask_b32_e32 v101, v113, v107, vcc
	v_mad_i64_i32 v[106:107], s[2:3], v106, s4, v[114:115]
	v_lshl_add_u64 v[108:109], v[108:109], 0, v[116:117]
	v_pk_mul_f32 v[94:95], v[0:1], v[94:95] op_sel_hi:[0,1]
	v_pk_mul_f32 v[92:93], v[0:1], v[92:93] op_sel_hi:[0,1]
	v_pk_mul_f32 v[90:91], v[0:1], v[90:91] op_sel_hi:[0,1]
	v_pk_mul_f32 v[88:89], v[88:89], v[0:1] op_sel_hi:[1,0]
	v_pk_mul_f32 v[86:87], v[86:87], v[0:1] op_sel_hi:[1,0]
	v_pk_mul_f32 v[84:85], v[84:85], v[0:1] op_sel_hi:[1,0]
	v_cndmask_b32_e32 v105, v105, v113, vcc
	v_cndmask_b32_e32 v104, v104, v112, vcc
	v_lshl_add_u64 v[106:107], v[106:107], 0, v[116:117]
	global_store_dwordx4 v[108:109], v[98:101], off nt
	global_store_dwordx4 v[106:107], v[102:105], off nt
	v_pk_mul_f32 v[96:97], v[0:1], v[96:97] op_sel_hi:[0,1]
	v_cvt_pk_bf16_f32 v94, v94, v95
	v_cvt_pk_bf16_f32 v95, v96, v97
	v_cvt_pk_bf16_f32 v90, v90, v91
	v_cvt_pk_bf16_f32 v91, v92, v93
	v_pk_mul_f32 v[82:83], v[82:83], v[0:1] op_sel_hi:[1,0]
	v_cvt_pk_bf16_f32 v86, v86, v87
	v_cvt_pk_bf16_f32 v87, v88, v89
	v_mov_b32_e32 v92, v1
	v_cvt_pk_bf16_f32 v88, v82, v83
	v_cvt_pk_bf16_f32 v89, v84, v85
	v_cndmask_b32_e32 v85, v94, v86, vcc
	v_cndmask_b32_e32 v82, v91, v89, vcc
	v_cndmask_b32_e32 v83, v95, v87, vcc
	v_cndmask_b32_e32 v84, v90, v88, vcc
	v_mov_b32_dpp v92, v85 row_ror:8 row_mask:0xf bank_mask:0xf
	v_mov_b32_e32 v93, v1
	v_mov_b32_e32 v96, v1
	v_mov_b32_e32 v97, v1
	v_mov_b32_dpp v93, v83 row_ror:8 row_mask:0xf bank_mask:0xf
	v_mov_b32_dpp v96, v84 row_ror:8 row_mask:0xf bank_mask:0xf
	v_mov_b32_dpp v97, v82 row_ror:8 row_mask:0xf bank_mask:0xf
; __device__ __forceinline__ unsigned cvt_pk_bf16(float lo, float hi) { unsigned r; asm volatile("v_cvt_pk_bf16_f32 %0, %1, %2" : "=v"(r) : "v"(lo), "v"(hi)); return r; }
;     __device__ __forceinline__ void operator()(f32x4 (&acc)[2][2][4][2], const Unit& u, int wr, int wc, int fr, int fq) const {
;     ...
;         for (int ai = 0; ai < 2; ++ai)
; #pragma unroll
;             for (int m = 0; m < 4; ++m) {
;                 u32x4 w[2];
; #pragma unroll
;                 for (int bj = 0; bj < 2; ++bj) { f32x4 v0 = acc[ai][bj][m][0], v1 = acc[ai][bj][m][1];
;                     if (act == 1) {
; #pragma unroll
;                         for (int e = 0; e < 4; ++e) { float a = fmaxf(v0[e], 0.f), b = fmaxf(v1[e], 0.f); v0[e] = a * a; v1[e] = b * b; } }
;                     v0 = v0 * sc; v1 = v1 * sc; w[bj].x = cvt_pk_bf16(v0[0], v0[1]); w[bj].y = cvt_pk_bf16(v0[2], v0[3]); w[bj].z = cvt_pk_bf16(v1[0], v1[1]); w[bj].w = cvt_pk_bf16(v1[2], v1[3]); }
;                 const u32x4 snd = hi ? w[0] : w[1]; u32x4 rcv;
;                 rcv.x = (unsigned)__builtin_amdgcn_update_dpp(0, (int)snd.x, 0x128, 0xF, 0xF, false); rcv.y = (unsigned)__builtin_amdgcn_update_dpp(0, (int)snd.y, 0x128, 0xF, 0xF, false);
;                 rcv.z = (unsigned)__builtin_amdgcn_update_dpp(0, (int)snd.z, 0x128, 0xF, 0xF, false); rcv.w = (unsigned)__builtin_amdgcn_update_dpp(0, (int)snd.w, 0x128, 0xF, 0xF, false);
;                 const u32x4 o1 = hi ? rcv : w[0], o2 = hi ? w[1] : rcv;
;                 const int r1 = rbase + ai * HALF + m * 16;
;                 bf16_t* p1 = O + (size_t)(r1 & rowmask) * ldc + colA; bf16_t* p2 = O + (size_t)((r1 + 8) & rowmask) * ldc + colA;
;                 if (O) { *(u32x4*)p1 = o1; *(u32x4*)p2 = o2; } else asm volatile("" :: "v"(o1), "v"(o2));
	v_cndmask_b32_e32 v82, v92, v94, vcc
	v_cndmask_b32_e32 v86, v86, v92, vcc
	v_or_b32_e32 v92, 32, v130
	v_cndmask_b32_e32 v83, v93, v95, vcc
	v_cndmask_b32_e32 v84, v96, v90, vcc
	v_cndmask_b32_e32 v87, v87, v93, vcc
	v_or_b32_e32 v90, 40, v130
	v_mad_i64_i32 v[92:93], s[2:3], v92, s4, v[114:115]
	v_cndmask_b32_e32 v85, v97, v91, vcc
	v_mad_i64_i32 v[90:91], s[2:3], v90, s4, v[114:115]
	v_lshl_add_u64 v[92:93], v[92:93], 0, v[116:117]
	v_pk_mul_f32 v[78:79], v[0:1], v[78:79] op_sel_hi:[0,1]
	v_pk_mul_f32 v[76:77], v[0:1], v[76:77] op_sel_hi:[0,1]
	v_pk_mul_f32 v[74:75], v[0:1], v[74:75] op_sel_hi:[0,1]
	v_pk_mul_f32 v[72:73], v[72:73], v[0:1] op_sel_hi:[1,0]
	v_pk_mul_f32 v[70:71], v[70:71], v[0:1] op_sel_hi:[1,0]
	v_pk_mul_f32 v[68:69], v[68:69], v[0:1] op_sel_hi:[1,0]
	v_cndmask_b32_e32 v89, v89, v97, vcc
	v_cndmask_b32_e32 v88, v88, v96, vcc
	v_lshl_add_u64 v[90:91], v[90:91], 0, v[116:117]
	global_store_dwordx4 v[92:93], v[82:85], off nt
	global_store_dwordx4 v[90:91], v[86:89], off nt
	v_pk_mul_f32 v[80:81], v[0:1], v[80:81] op_sel_hi:[0,1]
	v_cvt_pk_bf16_f32 v78, v78, v79
	v_cvt_pk_bf16_f32 v79, v80, v81
	v_cvt_pk_bf16_f32 v74, v74, v75
	v_cvt_pk_bf16_f32 v75, v76, v77
	v_pk_mul_f32 v[66:67], v[66:67], v[0:1] op_sel_hi:[1,0]
	v_cvt_pk_bf16_f32 v70, v70, v71
	v_cvt_pk_bf16_f32 v71, v72, v73
	v_mov_b32_e32 v76, v1
	v_cvt_pk_bf16_f32 v72, v66, v67
	v_cvt_pk_bf16_f32 v73, v68, v69
	v_cndmask_b32_e32 v69, v78, v70, vcc
	v_cndmask_b32_e32 v66, v75, v73, vcc
	v_cndmask_b32_e32 v67, v79, v71, vcc
	v_cndmask_b32_e32 v68, v74, v72, vcc
	v_mov_b32_dpp v76, v69 row_ror:8 row_mask:0xf bank_mask:0xf
	v_mov_b32_e32 v77, v1
	v_mov_b32_e32 v80, v1
	v_mov_b32_e32 v81, v1
	v_mov_b32_dpp v77, v67 row_ror:8 row_mask:0xf bank_mask:0xf
	v_mov_b32_dpp v80, v68 row_ror:8 row_mask:0xf bank_mask:0xf
	v_mov_b32_dpp v81, v66 row_ror:8 row_mask:0xf bank_mask:0xf
	v_cndmask_b32_e32 v66, v76, v78, vcc
	v_cndmask_b32_e32 v70, v70, v76, vcc
	v_or_b32_e32 v76, 48, v130
	v_cndmask_b32_e32 v67, v77, v79, vcc
	v_cndmask_b32_e32 v68, v80, v74, vcc
	v_cndmask_b32_e32 v71, v71, v77, vcc
	v_or_b32_e32 v74, 56, v130
	v_mad_i64_i32 v[76:77], s[2:3], v76, s4, v[114:115]
	v_cndmask_b32_e32 v69, v81, v75, vcc
	v_mad_i64_i32 v[74:75], s[2:3], v74, s4, v[114:115]
	v_lshl_add_u64 v[76:77], v[76:77], 0, v[116:117]
	v_pk_mul_f32 v[64:65], v[0:1], v[64:65] op_sel_hi:[0,1]
	v_pk_mul_f32 v[62:63], v[0:1], v[62:63] op_sel_hi:[0,1]
	v_pk_mul_f32 v[60:61], v[0:1], v[60:61] op_sel_hi:[0,1]
	v_pk_mul_f32 v[58:59], v[0:1], v[58:59] op_sel_hi:[0,1]
	v_pk_mul_f32 v[56:57], v[56:57], v[0:1] op_sel_hi:[1,0]
	v_pk_mul_f32 v[54:55], v[54:55], v[0:1] op_sel_hi:[1,0]
	v_pk_mul_f32 v[52:53], v[52:53], v[0:1] op_sel_hi:[1,0]
	v_pk_mul_f32 v[50:51], v[50:51], v[0:1] op_sel_hi:[1,0]
	v_cndmask_b32_e32 v73, v73, v81, vcc
	v_cndmask_b32_e32 v72, v72, v80, vcc
	v_lshl_add_u64 v[74:75], v[74:75], 0, v[116:117]
	global_store_dwordx4 v[76:77], v[66:69], off nt
	global_store_dwordx4 v[74:75], v[70:73], off nt
	v_cvt_pk_bf16_f32 v62, v62, v63
	v_cvt_pk_bf16_f32 v63, v64, v65
	v_cvt_pk_bf16_f32 v58, v58, v59
	v_cvt_pk_bf16_f32 v59, v60, v61
	v_cvt_pk_bf16_f32 v54, v54, v55
	v_cvt_pk_bf16_f32 v55, v56, v57
	v_cvt_pk_bf16_f32 v56, v50, v51
	v_cvt_pk_bf16_f32 v57, v52, v53
	v_mov_b32_e32 v60, v1
	v_cndmask_b32_e32 v51, v63, v55, vcc
	v_cndmask_b32_e32 v52, v58, v56, vcc
	v_cndmask_b32_e32 v53, v62, v54, vcc
	v_mov_b32_e32 v61, v1
	v_mov_b32_e32 v64, v1
	v_add_u32_e32 v66, 0x80, v130
	v_cndmask_b32_e32 v50, v59, v57, vcc
	v_mov_b32_dpp v60, v53 row_ror:8 row_mask:0xf bank_mask:0xf
	v_mov_b32_dpp v61, v51 row_ror:8 row_mask:0xf bank_mask:0xf
	v_mov_b32_dpp v64, v52 row_ror:8 row_mask:0xf bank_mask:0xf
	v_mov_b32_e32 v65, v1
	v_cndmask_b32_e32 v51, v61, v63, vcc
	v_cndmask_b32_e32 v52, v64, v58, vcc
	v_mov_b32_dpp v65, v50 row_ror:8 row_mask:0xf bank_mask:0xf
	v_cndmask_b32_e32 v50, v60, v62, vcc
	v_cndmask_b32_e32 v55, v55, v61, vcc
	v_cndmask_b32_e32 v54, v54, v60, vcc
	v_add_u32_e32 v58, 0x88, v130
	v_mad_i64_i32 v[60:61], s[2:3], v66, s4, v[114:115]
	v_cndmask_b32_e32 v53, v65, v59, vcc
	v_mad_i64_i32 v[58:59], s[2:3], v58, s4, v[114:115]
	v_lshl_add_u64 v[60:61], v[60:61], 0, v[116:117]
	v_pk_mul_f32 v[46:47], v[0:1], v[46:47] op_sel_hi:[0,1]
	v_pk_mul_f32 v[44:45], v[0:1], v[44:45] op_sel_hi:[0,1]
	v_pk_mul_f32 v[42:43], v[0:1], v[42:43] op_sel_hi:[0,1]
	v_pk_mul_f32 v[40:41], v[40:41], v[0:1] op_sel_hi:[1,0]
	v_pk_mul_f32 v[38:39], v[38:39], v[0:1] op_sel_hi:[1,0]
	v_pk_mul_f32 v[36:37], v[36:37], v[0:1] op_sel_hi:[1,0]
	v_cndmask_b32_e32 v57, v57, v65, vcc
	v_cndmask_b32_e32 v56, v56, v64, vcc
	v_lshl_add_u64 v[58:59], v[58:59], 0, v[116:117]
	global_store_dwordx4 v[60:61], v[50:53], off nt
	global_store_dwordx4 v[58:59], v[54:57], off nt
	v_pk_mul_f32 v[48:49], v[0:1], v[48:49] op_sel_hi:[0,1]
	v_cvt_pk_bf16_f32 v46, v46, v47
	v_cvt_pk_bf16_f32 v47, v48, v49
	v_cvt_pk_bf16_f32 v42, v42, v43
	v_cvt_pk_bf16_f32 v43, v44, v45
	v_pk_mul_f32 v[34:35], v[34:35], v[0:1] op_sel_hi:[1,0]
	v_cvt_pk_bf16_f32 v38, v38, v39
	v_cvt_pk_bf16_f32 v39, v40, v41
; __device__ __forceinline__ unsigned cvt_pk_bf16(float lo, float hi) { unsigned r; asm volatile("v_cvt_pk_bf16_f32 %0, %1, %2" : "=v"(r) : "v"(lo), "v"(hi)); return r; }
;     __device__ __forceinline__ void operator()(f32x4 (&acc)[2][2][4][2], const Unit& u, int wr, int wc, int fr, int fq) const {
;     ...
;         for (int ai = 0; ai < 2; ++ai)
; #pragma unroll
;             for (int m = 0; m < 4; ++m) {
;                 u32x4 w[2];
; #pragma unroll
;                 for (int bj = 0; bj < 2; ++bj) { f32x4 v0 = acc[ai][bj][m][0], v1 = acc[ai][bj][m][1];
;                     if (act == 1) {
; #pragma unroll
;                         for (int e = 0; e < 4; ++e) { float a = fmaxf(v0[e], 0.f), b = fmaxf(v1[e], 0.f); v0[e] = a * a; v1[e] = b * b; } }
;                     v0 = v0 * sc; v1 = v1 * sc; w[bj].x = cvt_pk_bf16(v0[0], v0[1]); w[bj].y = cvt_pk_bf16(v0[2], v0[3]); w[bj].z = cvt_pk_bf16(v1[0], v1[1]); w[bj].w = cvt_pk_bf16(v1[2], v1[3]); }
;                 const u32x4 snd = hi ? w[0] : w[1]; u32x4 rcv;
;                 rcv.x = (unsigned)__builtin_amdgcn_update_dpp(0, (int)snd.x, 0x128, 0xF, 0xF, false); rcv.y = (unsigned)__builtin_amdgcn_update_dpp(0, (int)snd.y, 0x128, 0xF, 0xF, false);
;                 rcv.z = (unsigned)__builtin_amdgcn_update_dpp(0, (int)snd.z, 0x128, 0xF, 0xF, false); rcv.w = (unsigned)__builtin_amdgcn_update_dpp(0, (int)snd.w, 0x128, 0xF, 0xF, false);
;                 const u32x4 o1 = hi ? rcv : w[0], o2 = hi ? w[1] : rcv;
;                 const int r1 = rbase + ai * HALF + m * 16;
;                 bf16_t* p1 = O + (size_t)(r1 & rowmask) * ldc + colA; bf16_t* p2 = O + (size_t)((r1 + 8) & rowmask) * ldc + colA;
;                 if (O) { *(u32x4*)p1 = o1; *(u32x4*)p2 = o2; } else asm volatile("" :: "v"(o1), "v"(o2));
	v_mov_b32_e32 v44, v1
	v_cvt_pk_bf16_f32 v40, v34, v35
	v_cvt_pk_bf16_f32 v41, v36, v37
	v_cndmask_b32_e32 v37, v46, v38, vcc
	v_cndmask_b32_e32 v34, v43, v41, vcc
	v_cndmask_b32_e32 v35, v47, v39, vcc
	v_cndmask_b32_e32 v36, v42, v40, vcc
	v_mov_b32_dpp v44, v37 row_ror:8 row_mask:0xf bank_mask:0xf
	v_mov_b32_e32 v45, v1
	v_mov_b32_e32 v48, v1
	v_mov_b32_e32 v49, v1
	v_mov_b32_dpp v45, v35 row_ror:8 row_mask:0xf bank_mask:0xf
	v_mov_b32_dpp v48, v36 row_ror:8 row_mask:0xf bank_mask:0xf
	v_mov_b32_dpp v49, v34 row_ror:8 row_mask:0xf bank_mask:0xf
	v_cndmask_b32_e32 v34, v44, v46, vcc
	v_cndmask_b32_e32 v38, v38, v44, vcc
	v_add_u32_e32 v44, 0x90, v130
	v_cndmask_b32_e32 v35, v45, v47, vcc
	v_cndmask_b32_e32 v36, v48, v42, vcc
	v_cndmask_b32_e32 v39, v39, v45, vcc
	v_add_u32_e32 v42, 0x98, v130
	v_mad_i64_i32 v[44:45], s[2:3], v44, s4, v[114:115]
	v_cndmask_b32_e32 v37, v49, v43, vcc
	v_mad_i64_i32 v[42:43], s[2:3], v42, s4, v[114:115]
	v_lshl_add_u64 v[44:45], v[44:45], 0, v[116:117]
	v_pk_mul_f32 v[30:31], v[0:1], v[30:31] op_sel_hi:[0,1]
	v_pk_mul_f32 v[28:29], v[0:1], v[28:29] op_sel_hi:[0,1]
	v_pk_mul_f32 v[26:27], v[0:1], v[26:27] op_sel_hi:[0,1]
	v_pk_mul_f32 v[24:25], v[24:25], v[0:1] op_sel_hi:[1,0]
	v_pk_mul_f32 v[22:23], v[22:23], v[0:1] op_sel_hi:[1,0]
	v_pk_mul_f32 v[20:21], v[20:21], v[0:1] op_sel_hi:[1,0]
	v_cndmask_b32_e32 v41, v41, v49, vcc
	v_cndmask_b32_e32 v40, v40, v48, vcc
	v_lshl_add_u64 v[42:43], v[42:43], 0, v[116:117]
	global_store_dwordx4 v[44:45], v[34:37], off nt
	global_store_dwordx4 v[42:43], v[38:41], off nt
	v_pk_mul_f32 v[32:33], v[0:1], v[32:33] op_sel_hi:[0,1]
	v_cvt_pk_bf16_f32 v30, v30, v31
	v_cvt_pk_bf16_f32 v31, v32, v33
	v_cvt_pk_bf16_f32 v26, v26, v27
	v_cvt_pk_bf16_f32 v27, v28, v29
	v_pk_mul_f32 v[18:19], v[18:19], v[0:1] op_sel_hi:[1,0]
	v_cvt_pk_bf16_f32 v22, v22, v23
	v_cvt_pk_bf16_f32 v23, v24, v25
	v_mov_b32_e32 v28, v1
	v_cvt_pk_bf16_f32 v24, v18, v19
	v_cvt_pk_bf16_f32 v25, v20, v21
	v_cndmask_b32_e32 v21, v30, v22, vcc
	v_cndmask_b32_e32 v18, v27, v25, vcc
	v_cndmask_b32_e32 v19, v31, v23, vcc
	v_cndmask_b32_e32 v20, v26, v24, vcc
	v_mov_b32_dpp v28, v21 row_ror:8 row_mask:0xf bank_mask:0xf
	v_mov_b32_e32 v29, v1
	v_mov_b32_e32 v32, v1
	v_mov_b32_e32 v33, v1
	v_mov_b32_dpp v29, v19 row_ror:8 row_mask:0xf bank_mask:0xf
	v_mov_b32_dpp v32, v20 row_ror:8 row_mask:0xf bank_mask:0xf
	v_mov_b32_dpp v33, v18 row_ror:8 row_mask:0xf bank_mask:0xf
	v_cndmask_b32_e32 v18, v28, v30, vcc
	v_cndmask_b32_e32 v22, v22, v28, vcc
	v_add_u32_e32 v28, 0xa0, v130
	v_cndmask_b32_e32 v19, v29, v31, vcc
	v_cndmask_b32_e32 v20, v32, v26, vcc
	v_cndmask_b32_e32 v23, v23, v29, vcc
	v_add_u32_e32 v26, 0xa8, v130
	v_mad_i64_i32 v[28:29], s[2:3], v28, s4, v[114:115]
	v_cndmask_b32_e32 v21, v33, v27, vcc
	v_mad_i64_i32 v[26:27], s[2:3], v26, s4, v[114:115]
	v_lshl_add_u64 v[28:29], v[28:29], 0, v[116:117]
	v_pk_mul_f32 v[14:15], v[0:1], v[14:15] op_sel_hi:[0,1]
	v_pk_mul_f32 v[12:13], v[0:1], v[12:13] op_sel_hi:[0,1]
	v_pk_mul_f32 v[10:11], v[0:1], v[10:11] op_sel_hi:[0,1]
	v_pk_mul_f32 v[8:9], v[8:9], v[0:1] op_sel_hi:[1,0]
	v_pk_mul_f32 v[6:7], v[6:7], v[0:1] op_sel_hi:[1,0]
	v_pk_mul_f32 v[4:5], v[4:5], v[0:1] op_sel_hi:[1,0]
	v_pk_mul_f32 v[2:3], v[2:3], v[0:1] op_sel_hi:[1,0]
	v_cndmask_b32_e32 v25, v25, v33, vcc
	v_cndmask_b32_e32 v24, v24, v32, vcc
	v_lshl_add_u64 v[26:27], v[26:27], 0, v[116:117]
	global_store_dwordx4 v[28:29], v[18:21], off nt
	global_store_dwordx4 v[26:27], v[22:25], off nt
	v_pk_mul_f32 v[16:17], v[0:1], v[16:17] op_sel_hi:[0,1]
	v_cvt_pk_bf16_f32 v14, v14, v15
	v_cvt_pk_bf16_f32 v15, v16, v17
	v_cvt_pk_bf16_f32 v10, v10, v11
	v_cvt_pk_bf16_f32 v11, v12, v13
	v_cvt_pk_bf16_f32 v0, v6, v7
	v_cvt_pk_bf16_f32 v6, v8, v9
	v_cvt_pk_bf16_f32 v8, v2, v3
	v_cvt_pk_bf16_f32 v9, v4, v5
	v_mov_b32_e32 v12, v1
	v_cndmask_b32_e32 v3, v15, v6, vcc
	v_cndmask_b32_e32 v4, v10, v8, vcc
	v_cndmask_b32_e32 v5, v14, v0, vcc
	v_mov_b32_e32 v7, v1
	v_mov_b32_e32 v13, v1
	v_cndmask_b32_e32 v2, v11, v9, vcc
	v_mov_b32_dpp v12, v5 row_ror:8 row_mask:0xf bank_mask:0xf
	v_mov_b32_dpp v7, v3 row_ror:8 row_mask:0xf bank_mask:0xf
	v_mov_b32_dpp v13, v4 row_ror:8 row_mask:0xf bank_mask:0xf
	v_mov_b32_e32 v16, v1
	v_cndmask_b32_e32 v3, v7, v15, vcc
	v_cndmask_b32_e32 v4, v13, v10, vcc
	v_mov_b32_dpp v16, v2 row_ror:8 row_mask:0xf bank_mask:0xf
	v_cndmask_b32_e32 v7, v6, v7, vcc
	v_cndmask_b32_e32 v6, v0, v12, vcc
	v_add_u32_e32 v0, 0xb0, v130
	v_add_u32_e32 v10, 0xb8, v130
	v_cndmask_b32_e32 v5, v16, v11, vcc
	v_cndmask_b32_e32 v2, v12, v14, vcc
	v_cndmask_b32_e32 v8, v8, v13, vcc
	v_mad_i64_i32 v[10:11], s[2:3], v10, s4, v[114:115]
	v_mad_i64_i32 v[12:13], s[2:3], v0, s4, v[114:115]
	v_cndmask_b32_e32 v9, v9, v16, vcc
	v_lshl_add_u64 v[12:13], v[12:13], 0, v[116:117]
	s_mov_b64 s[2:3], -1
	s_andn2_b64 vcc, exec, s[0:1]
	v_lshl_add_u64 v[10:11], v[10:11], 0, v[116:117]
	global_store_dwordx4 v[12:13], v[2:5], off nt
	global_store_dwordx4 v[10:11], v[6:9], off nt
	s_cbranch_vccnz .LBB0_429
	s_andn2_b64 vcc, exec, s[6:7]
	s_cbranch_vccnz .LBB0_428
	s_barrier
	s_branch .LBB0_428

;     __device__ __forceinline__ void operator()(f32x4 (&acc)[2][2][4][2], const Unit& u, int wr, int wc, int fr, int fq) const {
;     ...
;         if (st) {
;             float muv[2][4], rsv[2][4];
; #pragma unroll
;             for (int ai = 0; ai < 2; ++ai)
; #pragma unroll
;                 for (int m = 0; m < 4; ++m) { const int row = row0 + ai * HALF + m * 16; const f32x2 sv = *(const f32x2*)(st + 2 * row); muv[ai][m] = sv.x; rsv[ai][m] = sv.y; }
; #pragma unroll
;             for (int ai = 0; ai < 2; ++ai)
; #pragma unroll
;                 for (int m = 0; m < 4; ++m) { const float mu = muv[ai][m] * (1.f / 1024.f); rsv[ai][m] = __builtin_amdgcn_rsqf(rsv[ai][m] * (1.f / 1024.f) - mu * mu + 1e-5f); muv[ai][m] = mu; }
; #pragma unroll
;             for (int bj = 0; bj < 2; ++bj) {
;                 const f32x4 c1a = *(const f32x4*)(c1 + col0 + bj * 32), c1b = *(const f32x4*)(c1 + col0 + bj * 32 + 4), c2a = *(const f32x4*)(c2 + col0 + bj * 32), c2b = *(const f32x4*)(c2 + col0 + bj * 32 + 4);
; #pragma unroll
;                 for (int ai = 0; ai < 2; ++ai)
; #pragma unroll
;                     for (int m = 0; m < 4; ++m) { const float mu = muv[ai][m], rstd = rsv[ai][m];
;                         acc[ai][bj][m][0] = (acc[ai][bj][m][0] - mu * c1a) * rstd + c2a; acc[ai][bj][m][1] = (acc[ai][bj][m][1] - mu * c1b) * rstd + c2b; }
.LBB0_661:
	v_lshlrev_b32_e32 v132, 1, v150
	v_ashrrev_i32_e32 v133, 31, v132
	s_add_i32 s25, s25, s57
	v_lshl_add_u64 v[132:133], v[132:133], 2, s[12:13]
	v_lshl_add_u32 v130, v151, 3, s25
	global_load_dwordx2 v[134:135], v[132:133], off
	global_load_dwordx2 v[136:137], v[132:133], off offset:128
	global_load_dwordx2 v[150:151], v[132:133], off offset:256
	global_load_dwordx2 v[154:155], v[132:133], off offset:384
	global_load_dwordx2 v[158:159], v[132:133], off offset:1024
	global_load_dwordx2 v[160:161], v[132:133], off offset:1152
	global_load_dwordx2 v[166:167], v[132:133], off offset:1280
	s_nop 0
	global_load_dwordx2 v[132:133], v[132:133], off offset:1408
	v_ashrrev_i32_e32 v131, 31, v130
	s_mov_b32 s0, 0x100000
	s_waitcnt vmcnt(0)
	v_pk_mul_f32 v[180:181], v[134:135], s[90:91] op_sel_hi:[1,0]
	s_nop 0
	v_fma_f32 v0, -v180, v180, v181
	v_add_f32_e32 v0, 0x3727c5ac, v0
	v_pk_mul_f32 v[162:163], v[154:155], s[90:91] op_sel_hi:[1,0]
	v_pk_mul_f32 v[154:155], v[158:159], s[90:91] op_sel_hi:[1,0]
	v_lshlrev_b64 v[158:159], 2, v[130:131]
	v_lshl_add_u64 v[190:191], s[88:89], 0, v[158:159]
	global_load_dwordx4 v[194:197], v[190:191], off offset:16
	global_load_dwordx4 v[198:201], v[190:191], off
	v_lshl_add_u64 v[192:193], s[16:17], 0, v[158:159]
	global_load_dwordx4 v[202:205], v[192:193], off offset:16
	global_load_dwordx4 v[206:209], v[192:193], off
	v_pk_mul_f32 v[174:175], v[136:137], s[90:91] op_sel_hi:[1,0]
	v_rsq_f32_e32 v178, v0
	v_fma_f32 v0, -v174, v174, v175
	v_add_f32_e32 v0, 0x3727c5ac, v0
	v_pk_mul_f32 v[168:169], v[150:151], s[90:91] op_sel_hi:[1,0]
	v_rsq_f32_e32 v176, v0
	v_fma_f32 v0, -v168, v168, v169
	v_add_f32_e32 v0, 0x3727c5ac, v0
	v_rsq_f32_e32 v172, v0
	v_fma_f32 v0, -v162, v162, v163
	v_add_f32_e32 v0, 0x3727c5ac, v0
	v_rsq_f32_e32 v164, v0
	v_fma_f32 v0, -v154, v154, v155
	v_add_f32_e32 v0, 0x3727c5ac, v0
	v_pk_mul_f32 v[150:151], v[160:161], s[90:91] op_sel_hi:[1,0]
	v_rsq_f32_e32 v156, v0
	v_fma_f32 v0, -v150, v150, v151
	v_add_f32_e32 v0, 0x3727c5ac, v0
	v_pk_mul_f32 v[134:135], v[166:167], s[90:91] op_sel_hi:[1,0]
	v_rsq_f32_e32 v152, v0
	v_fma_f32 v0, -v134, v134, v135
	v_add_f32_e32 v0, 0x3727c5ac, v0
	v_pk_mul_f32 v[132:133], v[132:133], s[90:91] op_sel_hi:[1,0]
	v_rsq_f32_e32 v136, v0
	v_fma_f32 v0, -v132, v132, v133
	v_add_f32_e32 v0, 0x3727c5ac, v0
	v_rsq_f32_e32 v0, v0
	s_waitcnt vmcnt(3)
	v_pk_fma_f32 v[122:123], v[180:181], v[194:195], v[122:123] op_sel_hi:[0,1,1] neg_lo:[1,0,0] neg_hi:[1,0,0]
	s_waitcnt vmcnt(2)
	v_pk_fma_f32 v[126:127], v[180:181], v[198:199], v[126:127] op_sel_hi:[0,1,1] neg_lo:[1,0,0] neg_hi:[1,0,0]
	v_pk_fma_f32 v[110:111], v[168:169], v[198:199], v[110:111] op_sel_hi:[0,1,1] neg_lo:[1,0,0] neg_hi:[1,0,0]
	v_pk_fma_f32 v[94:95], v[154:155], v[198:199], v[94:95] op_sel_hi:[0,1,1] neg_lo:[1,0,0] neg_hi:[1,0,0]
	v_pk_fma_f32 v[78:79], v[198:199], v[134:135], v[78:79] op_sel_hi:[1,0,1] neg_lo:[1,0,0] neg_hi:[1,0,0]
	v_pk_fma_f32 v[128:129], v[180:181], v[200:201], v[128:129] op_sel_hi:[0,1,1] neg_lo:[1,0,0] neg_hi:[1,0,0]
	s_waitcnt vmcnt(0)
	v_pk_fma_f32 v[186:187], v[178:179], v[126:127], v[206:207] op_sel_hi:[0,1,1]
	v_pk_fma_f32 v[120:121], v[174:175], v[200:201], v[120:121] op_sel_hi:[0,1,1] neg_lo:[1,0,0] neg_hi:[1,0,0]
	v_pk_fma_f32 v[112:113], v[168:169], v[200:201], v[112:113] op_sel_hi:[0,1,1] neg_lo:[1,0,0] neg_hi:[1,0,0]
	v_pk_fma_f32 v[126:127], v[172:173], v[110:111], v[206:207] op_sel_hi:[0,1,1]
	v_pk_fma_f32 v[104:105], v[162:163], v[200:201], v[104:105] op_sel_hi:[0,1,1] neg_lo:[1,0,0] neg_hi:[1,0,0]
	v_pk_fma_f32 v[96:97], v[154:155], v[200:201], v[96:97] op_sel_hi:[0,1,1] neg_lo:[1,0,0] neg_hi:[1,0,0]
	v_pk_fma_f32 v[110:111], v[94:95], v[156:157], v[206:207] op_sel_hi:[1,0,1]
	v_xor_b32_e32 v201, 0x80000000, v201
	v_xor_b32_e32 v200, 0x80000000, v200
	v_pk_fma_f32 v[94:95], v[78:79], v[136:137], v[206:207] op_sel_hi:[1,0,1]
	v_xor_b32_e32 v79, 0x80000000, v197
	v_xor_b32_e32 v78, 0x80000000, v196
	v_pk_fma_f32 v[124:125], v[180:181], v[196:197], v[124:125] op_sel_hi:[0,1,1] neg_lo:[1,0,0] neg_hi:[1,0,0]
	v_pk_fma_f32 v[118:119], v[174:175], v[198:199], v[118:119] op_sel_hi:[0,1,1] neg_lo:[1,0,0] neg_hi:[1,0,0]
	v_pk_fma_f32 v[114:115], v[174:175], v[194:195], v[114:115] op_sel_hi:[0,1,1] neg_lo:[1,0,0] neg_hi:[1,0,0]
	v_pk_fma_f32 v[116:117], v[174:175], v[196:197], v[116:117] op_sel_hi:[0,1,1] neg_lo:[1,0,0] neg_hi:[1,0,0]
	v_pk_fma_f32 v[106:107], v[168:169], v[194:195], v[106:107] op_sel_hi:[0,1,1] neg_lo:[1,0,0] neg_hi:[1,0,0]
	v_pk_fma_f32 v[108:109], v[168:169], v[196:197], v[108:109] op_sel_hi:[0,1,1] neg_lo:[1,0,0] neg_hi:[1,0,0]
	v_pk_fma_f32 v[102:103], v[162:163], v[198:199], v[102:103] op_sel_hi:[0,1,1] neg_lo:[1,0,0] neg_hi:[1,0,0]
	v_pk_fma_f32 v[98:99], v[162:163], v[194:195], v[98:99] op_sel_hi:[0,1,1] neg_lo:[1,0,0] neg_hi:[1,0,0]
	v_pk_fma_f32 v[100:101], v[162:163], v[196:197], v[100:101] op_sel_hi:[0,1,1] neg_lo:[1,0,0] neg_hi:[1,0,0]
	v_pk_fma_f32 v[90:91], v[154:155], v[194:195], v[90:91] op_sel_hi:[0,1,1] neg_lo:[1,0,0] neg_hi:[1,0,0]
	v_pk_fma_f32 v[92:93], v[154:155], v[196:197], v[92:93] op_sel_hi:[0,1,1] neg_lo:[1,0,0] neg_hi:[1,0,0]
	v_pk_fma_f32 v[86:87], v[198:199], v[150:151], v[86:87] op_sel_hi:[1,0,1] neg_lo:[1,0,0] neg_hi:[1,0,0]
	v_pk_fma_f32 v[88:89], v[200:201], v[150:151], v[88:89] op_sel_hi:[1,0,1]
	v_pk_fma_f32 v[82:83], v[150:151], v[194:195], v[82:83] op_sel_hi:[0,1,1] neg_lo:[1,0,0] neg_hi:[1,0,0]
	v_pk_fma_f32 v[84:85], v[150:151], v[196:197], v[84:85] op_sel_hi:[0,1,1] neg_lo:[1,0,0] neg_hi:[1,0,0]
	v_pk_fma_f32 v[80:81], v[200:201], v[134:135], v[80:81] op_sel_hi:[1,0,1]
;     __device__ __forceinline__ void operator()(f32x4 (&acc)[2][2][4][2], const Unit& u, int wr, int wc, int fr, int fq) const {
;     ...
;             for (int bj = 0; bj < 2; ++bj) {
;                 const f32x4 c1a = *(const f32x4*)(c1 + col0 + bj * 32), c1b = *(const f32x4*)(c1 + col0 + bj * 32 + 4), c2a = *(const f32x4*)(c2 + col0 + bj * 32), c2b = *(const f32x4*)(c2 + col0 + bj * 32 + 4);
; #pragma unroll
;                 for (int ai = 0; ai < 2; ++ai)
; #pragma unroll
;                     for (int m = 0; m < 4; ++m) { const float mu = muv[ai][m], rstd = rsv[ai][m];
;                         acc[ai][bj][m][0] = (acc[ai][bj][m][0] - mu * c1a) * rstd + c2a; acc[ai][bj][m][1] = (acc[ai][bj][m][1] - mu * c1b) * rstd + c2b; }
	v_pk_fma_f32 v[74:75], v[194:195], v[134:135], v[74:75] op_sel_hi:[1,0,1] neg_lo:[1,0,0] neg_hi:[1,0,0]
	v_pk_fma_f32 v[76:77], v[78:79], v[134:135], v[76:77] op_sel_hi:[1,0,1]
	v_pk_fma_f32 v[70:71], v[198:199], v[132:133], v[70:71] op_sel_hi:[1,0,1] neg_lo:[1,0,0] neg_hi:[1,0,0]
	v_pk_fma_f32 v[72:73], v[200:201], v[132:133], v[72:73] op_sel_hi:[1,0,1]
	v_pk_fma_f32 v[66:67], v[194:195], v[132:133], v[66:67] op_sel_hi:[1,0,1] neg_lo:[1,0,0] neg_hi:[1,0,0]
	v_pk_fma_f32 v[68:69], v[78:79], v[132:133], v[68:69] op_sel_hi:[1,0,1]
	v_pk_fma_f32 v[182:183], v[178:179], v[128:129], v[208:209] op_sel_hi:[0,1,1]
	v_pk_fma_f32 v[184:185], v[178:179], v[124:125], v[204:205] op_sel_hi:[0,1,1]
	v_pk_fma_f32 v[188:189], v[178:179], v[122:123], v[202:203] op_sel_hi:[0,1,1]
	v_pk_fma_f32 v[158:159], v[176:177], v[120:121], v[208:209] op_sel_hi:[0,1,1]
	v_pk_fma_f32 v[166:167], v[176:177], v[118:119], v[206:207] op_sel_hi:[0,1,1]
	v_pk_fma_f32 v[160:161], v[176:177], v[116:117], v[204:205] op_sel_hi:[0,1,1]
	v_pk_fma_f32 v[170:171], v[176:177], v[114:115], v[202:203] op_sel_hi:[0,1,1]
	v_pk_fma_f32 v[122:123], v[172:173], v[112:113], v[208:209] op_sel_hi:[0,1,1]
	v_pk_fma_f32 v[124:125], v[172:173], v[108:109], v[204:205] op_sel_hi:[0,1,1]
	v_pk_fma_f32 v[128:129], v[172:173], v[106:107], v[202:203] op_sel_hi:[0,1,1]
	v_pk_fma_f32 v[114:115], v[104:105], v[164:165], v[208:209] op_sel_hi:[1,0,1]
	v_pk_fma_f32 v[118:119], v[102:103], v[164:165], v[206:207] op_sel_hi:[1,0,1]
	v_pk_fma_f32 v[116:117], v[164:165], v[100:101], v[204:205] op_sel_hi:[0,1,1]
	v_pk_fma_f32 v[120:121], v[164:165], v[98:99], v[202:203] op_sel_hi:[0,1,1]
	v_pk_fma_f32 v[106:107], v[96:97], v[156:157], v[208:209] op_sel_hi:[1,0,1]
	v_pk_fma_f32 v[108:109], v[92:93], v[156:157], v[204:205] op_sel_hi:[1,0,1]
	v_pk_fma_f32 v[112:113], v[90:91], v[156:157], v[202:203] op_sel_hi:[1,0,1]
	v_pk_fma_f32 v[98:99], v[88:89], v[152:153], v[208:209] op_sel_hi:[1,0,1]
	v_pk_fma_f32 v[102:103], v[86:87], v[152:153], v[206:207] op_sel_hi:[1,0,1]
	v_pk_fma_f32 v[100:101], v[84:85], v[152:153], v[204:205] op_sel_hi:[1,0,1]
	v_pk_fma_f32 v[104:105], v[82:83], v[152:153], v[202:203] op_sel_hi:[1,0,1]
	v_pk_fma_f32 v[90:91], v[80:81], v[136:137], v[208:209] op_sel_hi:[1,0,1]
	v_pk_fma_f32 v[92:93], v[76:77], v[136:137], v[204:205] op_sel_hi:[1,0,1]
	v_pk_fma_f32 v[96:97], v[74:75], v[136:137], v[202:203] op_sel_hi:[1,0,1]
	v_pk_fma_f32 v[82:83], v[72:73], v[0:1], v[208:209] op_sel_hi:[1,0,1]
	v_pk_fma_f32 v[86:87], v[70:71], v[0:1], v[206:207] op_sel_hi:[1,0,1]
	v_pk_fma_f32 v[84:85], v[68:69], v[0:1], v[204:205] op_sel_hi:[1,0,1]
	v_pk_fma_f32 v[88:89], v[66:67], v[0:1], v[202:203] op_sel_hi:[1,0,1]
	global_load_dwordx4 v[66:69], v[190:191], off offset:144
	global_load_dwordx4 v[74:77], v[190:191], off offset:128
	global_load_dwordx4 v[70:73], v[192:193], off offset:144
	global_load_dwordx4 v[78:81], v[192:193], off offset:128
	s_waitcnt vmcnt(3)
	v_pk_fma_f32 v[58:59], v[180:181], v[66:67], v[58:59] op_sel_hi:[0,1,1] neg_lo:[1,0,0] neg_hi:[1,0,0]
	s_waitcnt vmcnt(2)
	v_pk_fma_f32 v[62:63], v[180:181], v[74:75], v[62:63] op_sel_hi:[0,1,1] neg_lo:[1,0,0] neg_hi:[1,0,0]
	v_pk_fma_f32 v[64:65], v[180:181], v[76:77], v[64:65] op_sel_hi:[0,1,1] neg_lo:[1,0,0] neg_hi:[1,0,0]
	v_pk_fma_f32 v[60:61], v[180:181], v[68:69], v[60:61] op_sel_hi:[0,1,1] neg_lo:[1,0,0] neg_hi:[1,0,0]
	v_pk_fma_f32 v[50:51], v[174:175], v[66:67], v[50:51] op_sel_hi:[0,1,1] neg_lo:[1,0,0] neg_hi:[1,0,0]
	v_pk_fma_f32 v[52:53], v[174:175], v[68:69], v[52:53] op_sel_hi:[0,1,1] neg_lo:[1,0,0] neg_hi:[1,0,0]
	v_pk_fma_f32 v[46:47], v[168:169], v[74:75], v[46:47] op_sel_hi:[0,1,1] neg_lo:[1,0,0] neg_hi:[1,0,0]
	v_pk_fma_f32 v[44:45], v[168:169], v[68:69], v[44:45] op_sel_hi:[0,1,1] neg_lo:[1,0,0] neg_hi:[1,0,0]
	v_pk_fma_f32 v[38:39], v[162:163], v[74:75], v[38:39] op_sel_hi:[0,1,1] neg_lo:[1,0,0] neg_hi:[1,0,0]
	v_pk_fma_f32 v[34:35], v[162:163], v[66:67], v[34:35] op_sel_hi:[0,1,1] neg_lo:[1,0,0] neg_hi:[1,0,0]
	v_pk_fma_f32 v[26:27], v[154:155], v[66:67], v[26:27] op_sel_hi:[0,1,1] neg_lo:[1,0,0] neg_hi:[1,0,0]
	v_pk_fma_f32 v[28:29], v[154:155], v[68:69], v[28:29] op_sel_hi:[0,1,1] neg_lo:[1,0,0] neg_hi:[1,0,0]
	v_pk_fma_f32 v[22:23], v[150:151], v[74:75], v[22:23] op_sel_hi:[0,1,1] neg_lo:[1,0,0] neg_hi:[1,0,0]
	v_pk_fma_f32 v[20:21], v[150:151], v[68:69], v[20:21] op_sel_hi:[0,1,1] neg_lo:[1,0,0] neg_hi:[1,0,0]
	v_pk_fma_f32 v[14:15], v[134:135], v[74:75], v[14:15] op_sel_hi:[0,1,1] neg_lo:[1,0,0] neg_hi:[1,0,0]
	v_pk_fma_f32 v[10:11], v[134:135], v[66:67], v[10:11] op_sel_hi:[0,1,1] neg_lo:[1,0,0] neg_hi:[1,0,0]
	s_waitcnt vmcnt(0)
; __device__ __forceinline__ unsigned cvt_pk_bf16(float lo, float hi) { unsigned r; asm volatile("v_cvt_pk_bf16_f32 %0, %1, %2" : "=v"(r) : "v"(lo), "v"(hi)); return r; }
;     __device__ __forceinline__ void operator()(f32x4 (&acc)[2][2][4][2], const Unit& u, int wr, int wc, int fr, int fq) const {
;     ...
;                         acc[ai][bj][m][0] = (acc[ai][bj][m][0] - mu * c1a) * rstd + c2a; acc[ai][bj][m][1] = (acc[ai][bj][m][1] - mu * c1b) * rstd + c2b; }
;             }
;         }
;         const float sc = (colt < scale_cols) ? QSCALE : 1.f;
;         const bool hi = (fr & 8) != 0;
;         const int colA = col0 + (hi ? 32 : 0);
;         const int rbase = u.pm * BM + wr * 64 + (fr & 7);
; #pragma unroll
;         for (int ai = 0; ai < 2; ++ai)
; #pragma unroll
;             for (int m = 0; m < 4; ++m) {
;                 u32x4 w[2];
; #pragma unroll
;                 for (int bj = 0; bj < 2; ++bj) { f32x4 v0 = acc[ai][bj][m][0], v1 = acc[ai][bj][m][1];
;                     if (act == 1) {
; #pragma unroll
;                         for (int e = 0; e < 4; ++e) { float a = fmaxf(v0[e], 0.f), b = fmaxf(v1[e], 0.f); v0[e] = a * a; v1[e] = b * b; } }
;                     v0 = v0 * sc; v1 = v1 * sc; w[bj].x = cvt_pk_bf16(v0[0], v0[1]); w[bj].y = cvt_pk_bf16(v0[2], v0[3]); w[bj].z = cvt_pk_bf16(v1[0], v1[1]); w[bj].w = cvt_pk_bf16(v1[2], v1[3]); }
;                 const u32x4 snd = hi ? w[0] : w[1]; u32x4 rcv;
;                 rcv.x = (unsigned)__builtin_amdgcn_update_dpp(0, (int)snd.x, 0x128, 0xF, 0xF, false); rcv.y = (unsigned)__builtin_amdgcn_update_dpp(0, (int)snd.y, 0x128, 0xF, 0xF, false);
;                 rcv.z = (unsigned)__builtin_amdgcn_update_dpp(0, (int)snd.z, 0x128, 0xF, 0xF, false); rcv.w = (unsigned)__builtin_amdgcn_update_dpp(0, (int)snd.w, 0x128, 0xF, 0xF, false);
;                 const u32x4 o1 = hi ? rcv : w[0], o2 = hi ? w[1] : rcv;
	v_pk_fma_f32 v[64:65], v[178:179], v[64:65], v[80:81] op_sel_hi:[0,1,1]
	v_pk_fma_f32 v[62:63], v[178:179], v[62:63], v[78:79] op_sel_hi:[0,1,1]
	v_pk_fma_f32 v[60:61], v[178:179], v[60:61], v[72:73] op_sel_hi:[0,1,1]
	v_pk_fma_f32 v[178:179], v[178:179], v[58:59], v[70:71] op_sel_hi:[0,1,1]
	v_pk_fma_f32 v[54:55], v[174:175], v[74:75], v[54:55] op_sel_hi:[0,1,1] neg_lo:[1,0,0] neg_hi:[1,0,0]
	v_pk_fma_f32 v[56:57], v[174:175], v[76:77], v[56:57] op_sel_hi:[0,1,1] neg_lo:[1,0,0] neg_hi:[1,0,0]
	v_pk_fma_f32 v[58:59], v[176:177], v[52:53], v[72:73] op_sel_hi:[0,1,1]
	v_pk_fma_f32 v[174:175], v[176:177], v[50:51], v[70:71] op_sel_hi:[0,1,1]
	v_pk_fma_f32 v[52:53], v[172:173], v[46:47], v[78:79] op_sel_hi:[0,1,1]
	v_pk_fma_f32 v[50:51], v[172:173], v[44:45], v[72:73] op_sel_hi:[0,1,1]
	v_pk_fma_f32 v[44:45], v[164:165], v[38:39], v[78:79] op_sel_hi:[0,1,1]
	v_pk_fma_f32 v[46:47], v[164:165], v[34:35], v[70:71] op_sel_hi:[0,1,1]
	v_pk_fma_f32 v[34:35], v[156:157], v[28:29], v[72:73] op_sel_hi:[0,1,1]
	v_pk_fma_f32 v[38:39], v[156:157], v[26:27], v[70:71] op_sel_hi:[0,1,1]
	v_pk_fma_f32 v[28:29], v[152:153], v[22:23], v[78:79] op_sel_hi:[0,1,1]
	v_pk_fma_f32 v[26:27], v[152:153], v[20:21], v[72:73] op_sel_hi:[0,1,1]
	v_pk_fma_f32 v[20:21], v[136:137], v[14:15], v[78:79] op_sel_hi:[0,1,1]
	v_pk_fma_f32 v[22:23], v[136:137], v[10:11], v[70:71] op_sel_hi:[0,1,1]
	v_pk_fma_f32 v[10:11], v[132:133], v[74:75], v[6:7] op_sel_hi:[0,1,1] neg_lo:[1,0,0] neg_hi:[1,0,0]
	v_pk_fma_f32 v[6:7], v[132:133], v[76:77], v[8:9] op_sel_hi:[0,1,1] neg_lo:[1,0,0] neg_hi:[1,0,0]
	v_pk_fma_f32 v[2:3], v[132:133], v[66:67], v[2:3] op_sel_hi:[0,1,1] neg_lo:[1,0,0] neg_hi:[1,0,0]
	v_pk_fma_f32 v[4:5], v[132:133], v[68:69], v[4:5] op_sel_hi:[0,1,1] neg_lo:[1,0,0] neg_hi:[1,0,0]
	v_max_f32_e32 v14, 0, v186
	v_max_f32_e32 v15, 0, v187
	v_pk_fma_f32 v[42:43], v[168:169], v[66:67], v[42:43] op_sel_hi:[0,1,1] neg_lo:[1,0,0] neg_hi:[1,0,0]
	v_pk_fma_f32 v[36:37], v[162:163], v[68:69], v[36:37] op_sel_hi:[0,1,1] neg_lo:[1,0,0] neg_hi:[1,0,0]
	v_pk_fma_f32 v[30:31], v[154:155], v[74:75], v[30:31] op_sel_hi:[0,1,1] neg_lo:[1,0,0] neg_hi:[1,0,0]
	v_pk_fma_f32 v[18:19], v[150:151], v[66:67], v[18:19] op_sel_hi:[0,1,1] neg_lo:[1,0,0] neg_hi:[1,0,0]
	v_pk_fma_f32 v[12:13], v[134:135], v[68:69], v[12:13] op_sel_hi:[0,1,1] neg_lo:[1,0,0] neg_hi:[1,0,0]
	v_pk_fma_f32 v[6:7], v[6:7], v[0:1], v[80:81] op_sel_hi:[1,0,1]
	v_pk_fma_f32 v[8:9], v[10:11], v[0:1], v[78:79] op_sel_hi:[1,0,1]
	v_pk_fma_f32 v[4:5], v[0:1], v[4:5], v[72:73] op_sel_hi:[0,1,1]
	v_pk_fma_f32 v[10:11], v[0:1], v[2:3], v[70:71] op_sel_hi:[0,1,1]
	v_and_b32_e32 v0, 8, v165
	v_pk_mul_f32 v[14:15], v[14:15], v[14:15]
	v_pk_fma_f32 v[180:181], v[176:177], v[54:55], v[78:79] op_sel_hi:[0,1,1]
	v_pk_fma_f32 v[54:55], v[172:173], v[42:43], v[70:71] op_sel_hi:[0,1,1]
	v_pk_fma_f32 v[42:43], v[164:165], v[36:37], v[72:73] op_sel_hi:[0,1,1]
	v_pk_fma_f32 v[36:37], v[156:157], v[30:31], v[78:79] op_sel_hi:[0,1,1]
	v_pk_fma_f32 v[30:31], v[152:153], v[18:19], v[70:71] op_sel_hi:[0,1,1]
	v_pk_fma_f32 v[18:19], v[136:137], v[12:13], v[72:73] op_sel_hi:[0,1,1]
	v_cmp_eq_u32_e32 vcc, 0, v0
	v_lshl_add_u32 v12, v0, 2, v130
	v_and_or_b32 v0, v165, 7, s54
	v_pk_mul_f32 v[14:15], s[6:7], v[14:15] op_sel_hi:[0,1]
	v_add_u32_e32 v2, s23, v0
	v_max_f32_e32 v66, 0, v188
	v_max_f32_e32 v67, 0, v189
	v_max_f32_e32 v68, 0, v182
	v_max_f32_e32 v70, 0, v184
	v_max_f32_e32 v69, 0, v183
	v_max_f32_e32 v71, 0, v185
	v_cvt_pk_bf16_f32 v0, v14, v15
	v_max_f32_e32 v14, 0, v62
	v_max_f32_e32 v62, 0, v178
	v_max_f32_e32 v15, 0, v63
	v_max_f32_e32 v63, 0, v179
	v_max_f32_e32 v64, 0, v64
	v_max_f32_e32 v60, 0, v60
	v_max_f32_e32 v65, 0, v65
	v_max_f32_e32 v61, 0, v61
	v_pk_mul_f32 v[68:69], v[68:69], v[68:69]
	v_pk_mul_f32 v[66:67], v[66:67], v[66:67]
	v_pk_mul_f32 v[70:71], v[70:71], v[70:71]
	v_pk_mul_f32 v[14:15], v[14:15], v[14:15]
	v_pk_mul_f32 v[64:65], v[64:65], v[64:65]
	v_pk_mul_f32 v[62:63], v[62:63], v[62:63]
	v_pk_mul_f32 v[60:61], v[60:61], v[60:61]
	v_pk_mul_f32 v[68:69], s[6:7], v[68:69] op_sel_hi:[0,1]
	v_pk_mul_f32 v[70:71], s[6:7], v[70:71] op_sel_hi:[0,1]
	v_pk_mul_f32 v[66:67], s[6:7], v[66:67] op_sel_hi:[0,1]
	v_pk_mul_f32 v[64:65], s[6:7], v[64:65] op_sel_hi:[0,1]
	v_pk_mul_f32 v[14:15], s[6:7], v[14:15] op_sel_hi:[0,1]
	v_pk_mul_f32 v[60:61], s[6:7], v[60:61] op_sel_hi:[0,1]
	v_pk_mul_f32 v[62:63], s[6:7], v[62:63] op_sel_hi:[0,1]
	v_cvt_pk_bf16_f32 v3, v68, v69
	v_cvt_pk_bf16_f32 v66, v66, v67
	v_cvt_pk_bf16_f32 v67, v70, v71
	v_cvt_pk_bf16_f32 v14, v14, v15
	v_cvt_pk_bf16_f32 v15, v64, v65
	v_cvt_pk_bf16_f32 v68, v62, v63
	v_cvt_pk_bf16_f32 v64, v60, v61
	v_mov_b32_e32 v69, v1
	v_cndmask_b32_e32 v60, v67, v64, vcc
	v_cndmask_b32_e32 v63, v0, v14, vcc
	v_mov_b32_e32 v71, v1
	v_cndmask_b32_e32 v61, v3, v15, vcc
	v_mov_b32_dpp v69, v63 row_ror:8 row_mask:0xf bank_mask:0xf
	v_mov_b32_e32 v65, v1
	v_mov_b32_dpp v71, v60 row_ror:8 row_mask:0xf bank_mask:0xf
	v_cndmask_b32_e32 v63, v71, v67, vcc
	v_mov_b32_dpp v65, v61 row_ror:8 row_mask:0xf bank_mask:0xf
	v_cndmask_b32_e32 v67, v64, v71, vcc
	v_cndmask_b32_e32 v64, v14, v69, vcc
	v_or_b32_e32 v14, 8, v2
	v_cndmask_b32_e32 v61, v65, v3, vcc
	v_cndmask_b32_e32 v65, v15, v65, vcc
	v_ashrrev_i32_e32 v15, 31, v14
	v_ashrrev_i32_e32 v13, 31, v12
	v_cndmask_b32_e32 v62, v66, v68, vcc
	v_mov_b32_e32 v70, v1
	v_lshlrev_b64 v[14:15], 13, v[14:15]
	v_lshl_add_u64 v[14:15], s[84:85], 0, v[14:15]
	v_mov_b32_dpp v70, v62 row_ror:8 row_mask:0xf bank_mask:0xf
	v_lshlrev_b64 v[12:13], 1, v[12:13]
	v_ashrrev_i32_e32 v3, 31, v2
	v_cndmask_b32_e32 v60, v69, v0, vcc
	v_cndmask_b32_e32 v62, v70, v66, vcc
; __device__ __forceinline__ unsigned cvt_pk_bf16(float lo, float hi) { unsigned r; asm volatile("v_cvt_pk_bf16_f32 %0, %1, %2" : "=v"(r) : "v"(lo), "v"(hi)); return r; }
;     __device__ __forceinline__ void operator()(f32x4 (&acc)[2][2][4][2], const Unit& u, int wr, int wc, int fr, int fq) const {
;     ...
;         for (int ai = 0; ai < 2; ++ai)
; #pragma unroll
;             for (int m = 0; m < 4; ++m) {
;                 u32x4 w[2];
; #pragma unroll
;                 for (int bj = 0; bj < 2; ++bj) { f32x4 v0 = acc[ai][bj][m][0], v1 = acc[ai][bj][m][1];
;                     if (act == 1) {
; #pragma unroll
;                         for (int e = 0; e < 4; ++e) { float a = fmaxf(v0[e], 0.f), b = fmaxf(v1[e], 0.f); v0[e] = a * a; v1[e] = b * b; } }
;                     v0 = v0 * sc; v1 = v1 * sc; w[bj].x = cvt_pk_bf16(v0[0], v0[1]); w[bj].y = cvt_pk_bf16(v0[2], v0[3]); w[bj].z = cvt_pk_bf16(v1[0], v1[1]); w[bj].w = cvt_pk_bf16(v1[2], v1[3]); }
;                 const u32x4 snd = hi ? w[0] : w[1]; u32x4 rcv;
;                 rcv.x = (unsigned)__builtin_amdgcn_update_dpp(0, (int)snd.x, 0x128, 0xF, 0xF, false); rcv.y = (unsigned)__builtin_amdgcn_update_dpp(0, (int)snd.y, 0x128, 0xF, 0xF, false);
;                 rcv.z = (unsigned)__builtin_amdgcn_update_dpp(0, (int)snd.z, 0x128, 0xF, 0xF, false); rcv.w = (unsigned)__builtin_amdgcn_update_dpp(0, (int)snd.w, 0x128, 0xF, 0xF, false);
;                 const u32x4 o1 = hi ? rcv : w[0], o2 = hi ? w[1] : rcv;
;                 const int r1 = rbase + ai * HALF + m * 16;
;                 bf16_t* p1 = O + (size_t)(r1 & rowmask) * ldc + colA; bf16_t* p2 = O + (size_t)((r1 + 8) & rowmask) * ldc + colA;
;                 if (O) { *(u32x4*)p1 = o1; *(u32x4*)p2 = o2; } else asm volatile("" :: "v"(o1), "v"(o2));
	v_cndmask_b32_e32 v66, v68, v70, vcc
	v_lshl_add_u64 v[68:69], v[14:15], 0, v[12:13]
	v_lshlrev_b64 v[14:15], 13, v[2:3]
	v_lshl_add_u64 v[14:15], s[84:85], 0, v[14:15]
	v_lshl_add_u64 v[14:15], v[14:15], 0, v[12:13]
	global_store_dwordx4 v[14:15], v[60:63], off nt
	global_store_dwordx4 v[68:69], v[64:67], off nt
	v_pk_fma_f32 v[56:57], v[176:177], v[56:57], v[80:81] op_sel_hi:[0,1,1]
	v_max_f32_e32 v60, 0, v166
	v_max_f32_e32 v62, 0, v170
	v_max_f32_e32 v61, 0, v167
	v_max_f32_e32 v63, 0, v171
	v_max_f32_e32 v64, 0, v158
	v_max_f32_e32 v65, 0, v159
	v_pk_mul_f32 v[60:61], v[60:61], v[60:61]
	v_pk_mul_f32 v[64:65], v[64:65], v[64:65]
	v_pk_mul_f32 v[62:63], v[62:63], v[62:63]
	v_pk_mul_f32 v[64:65], s[6:7], v[64:65] op_sel_hi:[0,1]
	v_pk_mul_f32 v[60:61], s[6:7], v[60:61] op_sel_hi:[0,1]
	v_pk_mul_f32 v[62:63], s[6:7], v[62:63] op_sel_hi:[0,1]
	v_cvt_pk_bf16_f32 v0, v60, v61
	v_cvt_pk_bf16_f32 v3, v64, v65
	v_cvt_pk_bf16_f32 v64, v62, v63
	v_max_f32_e32 v60, 0, v180
	v_max_f32_e32 v62, 0, v174
	v_max_f32_e32 v61, 0, v181
	v_max_f32_e32 v63, 0, v175
	v_max_f32_e32 v58, 0, v58
	v_max_f32_e32 v59, 0, v59
	v_max_f32_e32 v66, 0, v160
	v_max_f32_e32 v67, 0, v161
	v_max_f32_e32 v56, 0, v56
	v_max_f32_e32 v57, 0, v57
	v_pk_mul_f32 v[60:61], v[60:61], v[60:61]
	v_pk_mul_f32 v[62:63], v[62:63], v[62:63]
	v_pk_mul_f32 v[58:59], v[58:59], v[58:59]
	v_pk_mul_f32 v[66:67], v[66:67], v[66:67]
	v_pk_mul_f32 v[56:57], v[56:57], v[56:57]
	v_pk_mul_f32 v[60:61], s[6:7], v[60:61] op_sel_hi:[0,1]
	v_pk_mul_f32 v[58:59], s[6:7], v[58:59] op_sel_hi:[0,1]
	v_pk_mul_f32 v[62:63], s[6:7], v[62:63] op_sel_hi:[0,1]
	v_pk_mul_f32 v[66:67], s[6:7], v[66:67] op_sel_hi:[0,1]
	v_cvt_pk_bf16_f32 v65, v66, v67
	v_pk_mul_f32 v[56:57], s[6:7], v[56:57] op_sel_hi:[0,1]
	v_cvt_pk_bf16_f32 v60, v60, v61
	v_cvt_pk_bf16_f32 v61, v56, v57
	v_cvt_pk_bf16_f32 v62, v62, v63
	v_cvt_pk_bf16_f32 v63, v58, v59
	v_mov_b32_e32 v68, v1
	v_cndmask_b32_e32 v58, v64, v62, vcc
	v_cndmask_b32_e32 v56, v65, v63, vcc
	v_cndmask_b32_e32 v59, v0, v60, vcc
	v_mov_b32_e32 v66, v1
	v_mov_b32_dpp v68, v58 row_ror:8 row_mask:0xf bank_mask:0xf
	v_mov_b32_e32 v69, v1
	v_cndmask_b32_e32 v57, v3, v61, vcc
	v_mov_b32_dpp v66, v59 row_ror:8 row_mask:0xf bank_mask:0xf
	v_mov_b32_e32 v67, v1
	v_mov_b32_dpp v69, v56 row_ror:8 row_mask:0xf bank_mask:0xf
	v_cndmask_b32_e32 v58, v68, v64, vcc
	v_or_b32_e32 v64, 16, v2
	v_mov_b32_dpp v67, v57 row_ror:8 row_mask:0xf bank_mask:0xf
	v_cndmask_b32_e32 v59, v69, v65, vcc
	v_cndmask_b32_e32 v56, v66, v0, vcc
	v_cndmask_b32_e32 v60, v60, v66, vcc
	v_or_b32_e32 v66, 24, v2
	v_ashrrev_i32_e32 v65, 31, v64
	v_cndmask_b32_e32 v57, v67, v3, vcc
	v_cndmask_b32_e32 v61, v61, v67, vcc
	v_ashrrev_i32_e32 v67, 31, v66
	v_lshlrev_b64 v[64:65], 13, v[64:65]
	v_lshlrev_b64 v[66:67], 13, v[66:67]
	v_lshl_add_u64 v[64:65], s[84:85], 0, v[64:65]
	v_pk_fma_f32 v[48:49], v[168:169], v[76:77], v[48:49] op_sel_hi:[0,1,1] neg_lo:[1,0,0] neg_hi:[1,0,0]
	v_lshl_add_u64 v[66:67], s[84:85], 0, v[66:67]
	v_lshl_add_u64 v[64:65], v[64:65], 0, v[12:13]
	v_pk_fma_f32 v[48:49], v[172:173], v[48:49], v[80:81] op_sel_hi:[0,1,1]
	v_cndmask_b32_e32 v63, v63, v69, vcc
	v_cndmask_b32_e32 v62, v62, v68, vcc
	v_lshl_add_u64 v[66:67], v[66:67], 0, v[12:13]
	global_store_dwordx4 v[64:65], v[56:59], off nt
	global_store_dwordx4 v[66:67], v[60:63], off nt
	v_max_f32_e32 v52, 0, v52
	v_max_f32_e32 v56, 0, v126
	v_max_f32_e32 v57, 0, v127
	v_max_f32_e32 v60, 0, v122
	v_max_f32_e32 v61, 0, v123
	v_max_f32_e32 v54, 0, v54
	v_max_f32_e32 v53, 0, v53
	v_max_f32_e32 v55, 0, v55
	v_max_f32_e32 v50, 0, v50
	v_max_f32_e32 v51, 0, v51
	v_max_f32_e32 v58, 0, v128
	v_max_f32_e32 v59, 0, v129
	v_max_f32_e32 v62, 0, v124
	v_max_f32_e32 v63, 0, v125
	v_pk_mul_f32 v[56:57], v[56:57], v[56:57]
	v_pk_mul_f32 v[60:61], v[60:61], v[60:61]
	v_max_f32_e32 v48, 0, v48
	v_max_f32_e32 v49, 0, v49
	v_pk_mul_f32 v[52:53], v[52:53], v[52:53]
	v_pk_mul_f32 v[54:55], v[54:55], v[54:55]
	v_pk_mul_f32 v[50:51], v[50:51], v[50:51]
	v_pk_mul_f32 v[58:59], v[58:59], v[58:59]
	v_pk_mul_f32 v[62:63], v[62:63], v[62:63]
	v_pk_mul_f32 v[60:61], s[6:7], v[60:61] op_sel_hi:[0,1]
	v_pk_mul_f32 v[56:57], s[6:7], v[56:57] op_sel_hi:[0,1]
	v_pk_mul_f32 v[48:49], v[48:49], v[48:49]
	v_pk_mul_f32 v[52:53], s[6:7], v[52:53] op_sel_hi:[0,1]
	v_pk_mul_f32 v[50:51], s[6:7], v[50:51] op_sel_hi:[0,1]
	v_pk_mul_f32 v[54:55], s[6:7], v[54:55] op_sel_hi:[0,1]
	v_pk_mul_f32 v[62:63], s[6:7], v[62:63] op_sel_hi:[0,1]
	v_pk_mul_f32 v[58:59], s[6:7], v[58:59] op_sel_hi:[0,1]
	v_cvt_pk_bf16_f32 v0, v56, v57
	v_cvt_pk_bf16_f32 v3, v60, v61
	v_cvt_pk_bf16_f32 v56, v58, v59
	v_cvt_pk_bf16_f32 v57, v62, v63
	v_pk_mul_f32 v[48:49], s[6:7], v[48:49] op_sel_hi:[0,1]
	v_cvt_pk_bf16_f32 v52, v52, v53
	v_cvt_pk_bf16_f32 v53, v48, v49
	v_cvt_pk_bf16_f32 v54, v54, v55
	v_cvt_pk_bf16_f32 v55, v50, v51
	v_mov_b32_e32 v60, v1
	v_cndmask_b32_e32 v50, v56, v54, vcc
	v_cndmask_b32_e32 v48, v57, v55, vcc
	v_cndmask_b32_e32 v51, v0, v52, vcc
	v_mov_b32_e32 v58, v1
	v_mov_b32_dpp v60, v50 row_ror:8 row_mask:0xf bank_mask:0xf
	v_mov_b32_e32 v61, v1
	v_cndmask_b32_e32 v49, v3, v53, vcc
	v_mov_b32_dpp v58, v51 row_ror:8 row_mask:0xf bank_mask:0xf
	v_mov_b32_e32 v59, v1
	v_mov_b32_dpp v61, v48 row_ror:8 row_mask:0xf bank_mask:0xf
	v_cndmask_b32_e32 v50, v60, v56, vcc
	v_or_b32_e32 v56, 32, v2
	v_mov_b32_dpp v59, v49 row_ror:8 row_mask:0xf bank_mask:0xf
	v_cndmask_b32_e32 v51, v61, v57, vcc
	v_cndmask_b32_e32 v48, v58, v0, vcc
	v_cndmask_b32_e32 v52, v52, v58, vcc
	v_or_b32_e32 v58, 40, v2
	v_ashrrev_i32_e32 v57, 31, v56
	v_cndmask_b32_e32 v49, v59, v3, vcc
	v_cndmask_b32_e32 v53, v53, v59, vcc
; __device__ __forceinline__ unsigned cvt_pk_bf16(float lo, float hi) { unsigned r; asm volatile("v_cvt_pk_bf16_f32 %0, %1, %2" : "=v"(r) : "v"(lo), "v"(hi)); return r; }
;     __device__ __forceinline__ void operator()(f32x4 (&acc)[2][2][4][2], const Unit& u, int wr, int wc, int fr, int fq) const {
;     ...
;                     for (int m = 0; m < 4; ++m) { const float mu = muv[ai][m], rstd = rsv[ai][m];
;                         acc[ai][bj][m][0] = (acc[ai][bj][m][0] - mu * c1a) * rstd + c2a; acc[ai][bj][m][1] = (acc[ai][bj][m][1] - mu * c1b) * rstd + c2b; }
;             }
;         }
;         const float sc = (colt < scale_cols) ? QSCALE : 1.f;
;         const bool hi = (fr & 8) != 0;
;         const int colA = col0 + (hi ? 32 : 0);
;         const int rbase = u.pm * BM + wr * 64 + (fr & 7);
; #pragma unroll
;         for (int ai = 0; ai < 2; ++ai)
; #pragma unroll
;             for (int m = 0; m < 4; ++m) {
;                 u32x4 w[2];
; #pragma unroll
;                 for (int bj = 0; bj < 2; ++bj) { f32x4 v0 = acc[ai][bj][m][0], v1 = acc[ai][bj][m][1];
;                     if (act == 1) {
; #pragma unroll
;                         for (int e = 0; e < 4; ++e) { float a = fmaxf(v0[e], 0.f), b = fmaxf(v1[e], 0.f); v0[e] = a * a; v1[e] = b * b; } }
;                     v0 = v0 * sc; v1 = v1 * sc; w[bj].x = cvt_pk_bf16(v0[0], v0[1]); w[bj].y = cvt_pk_bf16(v0[2], v0[3]); w[bj].z = cvt_pk_bf16(v1[0], v1[1]); w[bj].w = cvt_pk_bf16(v1[2], v1[3]); }
;                 const u32x4 snd = hi ? w[0] : w[1]; u32x4 rcv;
;                 rcv.x = (unsigned)__builtin_amdgcn_update_dpp(0, (int)snd.x, 0x128, 0xF, 0xF, false); rcv.y = (unsigned)__builtin_amdgcn_update_dpp(0, (int)snd.y, 0x128, 0xF, 0xF, false);
;                 rcv.z = (unsigned)__builtin_amdgcn_update_dpp(0, (int)snd.z, 0x128, 0xF, 0xF, false); rcv.w = (unsigned)__builtin_amdgcn_update_dpp(0, (int)snd.w, 0x128, 0xF, 0xF, false);
;                 const u32x4 o1 = hi ? rcv : w[0], o2 = hi ? w[1] : rcv;
;                 const int r1 = rbase + ai * HALF + m * 16;
;                 bf16_t* p1 = O + (size_t)(r1 & rowmask) * ldc + colA; bf16_t* p2 = O + (size_t)((r1 + 8) & rowmask) * ldc + colA;
;                 if (O) { *(u32x4*)p1 = o1; *(u32x4*)p2 = o2; } else asm volatile("" :: "v"(o1), "v"(o2));
	v_ashrrev_i32_e32 v59, 31, v58
	v_lshlrev_b64 v[56:57], 13, v[56:57]
	v_lshlrev_b64 v[58:59], 13, v[58:59]
	v_lshl_add_u64 v[56:57], s[84:85], 0, v[56:57]
	v_pk_fma_f32 v[40:41], v[162:163], v[76:77], v[40:41] op_sel_hi:[0,1,1] neg_lo:[1,0,0] neg_hi:[1,0,0]
	v_lshl_add_u64 v[58:59], s[84:85], 0, v[58:59]
	v_lshl_add_u64 v[56:57], v[56:57], 0, v[12:13]
	v_pk_fma_f32 v[40:41], v[164:165], v[40:41], v[80:81] op_sel_hi:[0,1,1]
	v_cndmask_b32_e32 v55, v55, v61, vcc
	v_cndmask_b32_e32 v54, v54, v60, vcc
	v_lshl_add_u64 v[58:59], v[58:59], 0, v[12:13]
	global_store_dwordx4 v[56:57], v[48:51], off nt
	global_store_dwordx4 v[58:59], v[52:55], off nt
	v_max_f32_e32 v44, 0, v44
	v_max_f32_e32 v48, 0, v118
	v_max_f32_e32 v49, 0, v119
	v_max_f32_e32 v52, 0, v114
	v_max_f32_e32 v53, 0, v115
	v_max_f32_e32 v46, 0, v46
	v_max_f32_e32 v45, 0, v45
	v_max_f32_e32 v47, 0, v47
	v_max_f32_e32 v42, 0, v42
	v_max_f32_e32 v43, 0, v43
	v_max_f32_e32 v50, 0, v120
	v_max_f32_e32 v51, 0, v121
	v_max_f32_e32 v54, 0, v116
	v_max_f32_e32 v55, 0, v117
	v_pk_mul_f32 v[48:49], v[48:49], v[48:49]
	v_pk_mul_f32 v[52:53], v[52:53], v[52:53]
	v_max_f32_e32 v40, 0, v40
	v_max_f32_e32 v41, 0, v41
	v_pk_mul_f32 v[44:45], v[44:45], v[44:45]
	v_pk_mul_f32 v[46:47], v[46:47], v[46:47]
	v_pk_mul_f32 v[42:43], v[42:43], v[42:43]
	v_pk_mul_f32 v[50:51], v[50:51], v[50:51]
	v_pk_mul_f32 v[54:55], v[54:55], v[54:55]
	v_pk_mul_f32 v[52:53], s[6:7], v[52:53] op_sel_hi:[0,1]
	v_pk_mul_f32 v[48:49], s[6:7], v[48:49] op_sel_hi:[0,1]
	v_pk_mul_f32 v[40:41], v[40:41], v[40:41]
	v_pk_mul_f32 v[44:45], s[6:7], v[44:45] op_sel_hi:[0,1]
	v_pk_mul_f32 v[42:43], s[6:7], v[42:43] op_sel_hi:[0,1]
	v_pk_mul_f32 v[46:47], s[6:7], v[46:47] op_sel_hi:[0,1]
	v_pk_mul_f32 v[54:55], s[6:7], v[54:55] op_sel_hi:[0,1]
	v_pk_mul_f32 v[50:51], s[6:7], v[50:51] op_sel_hi:[0,1]
	v_cvt_pk_bf16_f32 v0, v48, v49
	v_cvt_pk_bf16_f32 v3, v52, v53
	v_cvt_pk_bf16_f32 v48, v50, v51
	v_cvt_pk_bf16_f32 v49, v54, v55
	v_pk_mul_f32 v[40:41], s[6:7], v[40:41] op_sel_hi:[0,1]
	v_cvt_pk_bf16_f32 v44, v44, v45
	v_cvt_pk_bf16_f32 v45, v40, v41
	v_cvt_pk_bf16_f32 v46, v46, v47
	v_cvt_pk_bf16_f32 v47, v42, v43
	v_mov_b32_e32 v52, v1
	v_cndmask_b32_e32 v42, v48, v46, vcc
	v_cndmask_b32_e32 v40, v49, v47, vcc
	v_cndmask_b32_e32 v43, v0, v44, vcc
	v_mov_b32_e32 v50, v1
	v_mov_b32_dpp v52, v42 row_ror:8 row_mask:0xf bank_mask:0xf
	v_mov_b32_e32 v53, v1
	v_cndmask_b32_e32 v41, v3, v45, vcc
	v_mov_b32_dpp v50, v43 row_ror:8 row_mask:0xf bank_mask:0xf
	v_mov_b32_e32 v51, v1
	v_mov_b32_dpp v53, v40 row_ror:8 row_mask:0xf bank_mask:0xf
	v_cndmask_b32_e32 v42, v52, v48, vcc
	v_or_b32_e32 v48, 48, v2
	v_mov_b32_dpp v51, v41 row_ror:8 row_mask:0xf bank_mask:0xf
	v_cndmask_b32_e32 v43, v53, v49, vcc
	v_cndmask_b32_e32 v40, v50, v0, vcc
	v_cndmask_b32_e32 v44, v44, v50, vcc
	v_or_b32_e32 v50, 56, v2
	v_ashrrev_i32_e32 v49, 31, v48
	v_cndmask_b32_e32 v41, v51, v3, vcc
	v_cndmask_b32_e32 v45, v45, v51, vcc
	v_ashrrev_i32_e32 v51, 31, v50
	v_lshlrev_b64 v[48:49], 13, v[48:49]
	v_lshlrev_b64 v[50:51], 13, v[50:51]
	v_lshl_add_u64 v[48:49], s[84:85], 0, v[48:49]
	v_pk_fma_f32 v[32:33], v[154:155], v[76:77], v[32:33] op_sel_hi:[0,1,1] neg_lo:[1,0,0] neg_hi:[1,0,0]
	v_lshl_add_u64 v[50:51], s[84:85], 0, v[50:51]
	v_lshl_add_u64 v[48:49], v[48:49], 0, v[12:13]
	v_pk_fma_f32 v[32:33], v[156:157], v[32:33], v[80:81] op_sel_hi:[0,1,1]
	v_cndmask_b32_e32 v47, v47, v53, vcc
	v_cndmask_b32_e32 v46, v46, v52, vcc
	v_lshl_add_u64 v[50:51], v[50:51], 0, v[12:13]
	global_store_dwordx4 v[48:49], v[40:43], off nt
	global_store_dwordx4 v[50:51], v[44:47], off nt
	v_max_f32_e32 v36, 0, v36
	v_max_f32_e32 v40, 0, v110
	v_max_f32_e32 v41, 0, v111
	v_max_f32_e32 v44, 0, v106
	v_max_f32_e32 v45, 0, v107
	v_max_f32_e32 v38, 0, v38
	v_max_f32_e32 v37, 0, v37
	v_max_f32_e32 v39, 0, v39
	v_max_f32_e32 v34, 0, v34
	v_max_f32_e32 v35, 0, v35
	v_max_f32_e32 v42, 0, v112
	v_max_f32_e32 v43, 0, v113
	v_max_f32_e32 v46, 0, v108
	v_max_f32_e32 v47, 0, v109
	v_pk_mul_f32 v[40:41], v[40:41], v[40:41]
	v_pk_mul_f32 v[44:45], v[44:45], v[44:45]
	v_max_f32_e32 v32, 0, v32
	v_max_f32_e32 v33, 0, v33
	v_pk_mul_f32 v[36:37], v[36:37], v[36:37]
	v_pk_mul_f32 v[38:39], v[38:39], v[38:39]
	v_pk_mul_f32 v[34:35], v[34:35], v[34:35]
	v_pk_mul_f32 v[42:43], v[42:43], v[42:43]
	v_pk_mul_f32 v[46:47], v[46:47], v[46:47]
	v_pk_mul_f32 v[44:45], s[6:7], v[44:45] op_sel_hi:[0,1]
	v_pk_mul_f32 v[40:41], s[6:7], v[40:41] op_sel_hi:[0,1]
	v_pk_mul_f32 v[32:33], v[32:33], v[32:33]
	v_pk_mul_f32 v[36:37], s[6:7], v[36:37] op_sel_hi:[0,1]
	v_pk_mul_f32 v[34:35], s[6:7], v[34:35] op_sel_hi:[0,1]
	v_pk_mul_f32 v[38:39], s[6:7], v[38:39] op_sel_hi:[0,1]
	v_pk_mul_f32 v[46:47], s[6:7], v[46:47] op_sel_hi:[0,1]
	v_pk_mul_f32 v[42:43], s[6:7], v[42:43] op_sel_hi:[0,1]
	v_cvt_pk_bf16_f32 v0, v40, v41
	v_cvt_pk_bf16_f32 v3, v44, v45
	v_cvt_pk_bf16_f32 v40, v42, v43
	v_cvt_pk_bf16_f32 v41, v46, v47
	v_pk_mul_f32 v[32:33], s[6:7], v[32:33] op_sel_hi:[0,1]
	v_cvt_pk_bf16_f32 v36, v36, v37
	v_cvt_pk_bf16_f32 v37, v32, v33
	v_cvt_pk_bf16_f32 v38, v38, v39
	v_cvt_pk_bf16_f32 v39, v34, v35
	v_mov_b32_e32 v44, v1
	v_cndmask_b32_e32 v34, v40, v38, vcc
	v_cndmask_b32_e32 v32, v41, v39, vcc
	v_mov_b32_e32 v45, v1
	v_mov_b32_dpp v44, v34 row_ror:8 row_mask:0xf bank_mask:0xf
	v_cndmask_b32_e32 v35, v0, v36, vcc
	v_mov_b32_e32 v42, v1
	v_mov_b32_dpp v45, v32 row_ror:8 row_mask:0xf bank_mask:0xf
	v_cndmask_b32_e32 v34, v44, v40, vcc
	v_add_u32_e32 v40, 0x88, v2
	v_cndmask_b32_e32 v33, v3, v37, vcc
	v_mov_b32_dpp v42, v35 row_ror:8 row_mask:0xf bank_mask:0xf
	v_mov_b32_e32 v43, v1
	v_cndmask_b32_e32 v35, v45, v41, vcc
; __device__ __forceinline__ unsigned cvt_pk_bf16(float lo, float hi) { unsigned r; asm volatile("v_cvt_pk_bf16_f32 %0, %1, %2" : "=v"(r) : "v"(lo), "v"(hi)); return r; }
;     __device__ __forceinline__ void operator()(f32x4 (&acc)[2][2][4][2], const Unit& u, int wr, int wc, int fr, int fq) const {
;     ...
;                     for (int m = 0; m < 4; ++m) { const float mu = muv[ai][m], rstd = rsv[ai][m];
;                         acc[ai][bj][m][0] = (acc[ai][bj][m][0] - mu * c1a) * rstd + c2a; acc[ai][bj][m][1] = (acc[ai][bj][m][1] - mu * c1b) * rstd + c2b; }
;             }
;         }
;         const float sc = (colt < scale_cols) ? QSCALE : 1.f;
;         const bool hi = (fr & 8) != 0;
;         const int colA = col0 + (hi ? 32 : 0);
;         const int rbase = u.pm * BM + wr * 64 + (fr & 7);
; #pragma unroll
;         for (int ai = 0; ai < 2; ++ai)
; #pragma unroll
;             for (int m = 0; m < 4; ++m) {
;                 u32x4 w[2];
; #pragma unroll
;                 for (int bj = 0; bj < 2; ++bj) { f32x4 v0 = acc[ai][bj][m][0], v1 = acc[ai][bj][m][1];
;                     if (act == 1) {
; #pragma unroll
;                         for (int e = 0; e < 4; ++e) { float a = fmaxf(v0[e], 0.f), b = fmaxf(v1[e], 0.f); v0[e] = a * a; v1[e] = b * b; } }
;                     v0 = v0 * sc; v1 = v1 * sc; w[bj].x = cvt_pk_bf16(v0[0], v0[1]); w[bj].y = cvt_pk_bf16(v0[2], v0[3]); w[bj].z = cvt_pk_bf16(v1[0], v1[1]); w[bj].w = cvt_pk_bf16(v1[2], v1[3]); }
;                 const u32x4 snd = hi ? w[0] : w[1]; u32x4 rcv;
;                 rcv.x = (unsigned)__builtin_amdgcn_update_dpp(0, (int)snd.x, 0x128, 0xF, 0xF, false); rcv.y = (unsigned)__builtin_amdgcn_update_dpp(0, (int)snd.y, 0x128, 0xF, 0xF, false);
;                 rcv.z = (unsigned)__builtin_amdgcn_update_dpp(0, (int)snd.z, 0x128, 0xF, 0xF, false); rcv.w = (unsigned)__builtin_amdgcn_update_dpp(0, (int)snd.w, 0x128, 0xF, 0xF, false);
;                 const u32x4 o1 = hi ? rcv : w[0], o2 = hi ? w[1] : rcv;
;                 const int r1 = rbase + ai * HALF + m * 16;
;                 bf16_t* p1 = O + (size_t)(r1 & rowmask) * ldc + colA; bf16_t* p2 = O + (size_t)((r1 + 8) & rowmask) * ldc + colA;
;                 if (O) { *(u32x4*)p1 = o1; *(u32x4*)p2 = o2; } else asm volatile("" :: "v"(o1), "v"(o2));
	v_ashrrev_i32_e32 v41, 31, v40
	v_mov_b32_dpp v43, v33 row_ror:8 row_mask:0xf bank_mask:0xf
	v_cndmask_b32_e32 v32, v42, v0, vcc
	v_cndmask_b32_e32 v36, v36, v42, vcc
	v_lshlrev_b64 v[40:41], 13, v[40:41]
	v_add_co_u32_e64 v42, s[4:5], s0, v14
	v_pk_fma_f32 v[24:25], v[150:151], v[76:77], v[24:25] op_sel_hi:[0,1,1] neg_lo:[1,0,0] neg_hi:[1,0,0]
	v_cndmask_b32_e32 v33, v43, v3, vcc
	v_cndmask_b32_e32 v37, v37, v43, vcc
	v_lshl_add_u64 v[40:41], s[84:85], 0, v[40:41]
	v_addc_co_u32_e64 v43, s[4:5], 0, v15, s[4:5]
	v_pk_fma_f32 v[24:25], v[152:153], v[24:25], v[80:81] op_sel_hi:[0,1,1]
	v_cndmask_b32_e32 v39, v39, v45, vcc
	v_cndmask_b32_e32 v38, v38, v44, vcc
	v_lshl_add_u64 v[40:41], v[40:41], 0, v[12:13]
	global_store_dwordx4 v[42:43], v[32:35], off nt
	global_store_dwordx4 v[40:41], v[36:39], off nt
	v_max_f32_e32 v28, 0, v28
	v_max_f32_e32 v32, 0, v102
	v_max_f32_e32 v33, 0, v103
	v_max_f32_e32 v36, 0, v98
	v_max_f32_e32 v37, 0, v99
	v_max_f32_e32 v30, 0, v30
	v_max_f32_e32 v29, 0, v29
	v_max_f32_e32 v31, 0, v31
	v_max_f32_e32 v26, 0, v26
	v_max_f32_e32 v27, 0, v27
	v_max_f32_e32 v34, 0, v104
	v_max_f32_e32 v35, 0, v105
	v_max_f32_e32 v38, 0, v100
	v_max_f32_e32 v39, 0, v101
	v_pk_mul_f32 v[32:33], v[32:33], v[32:33]
	v_pk_mul_f32 v[36:37], v[36:37], v[36:37]
	v_max_f32_e32 v24, 0, v24
	v_max_f32_e32 v25, 0, v25
	v_pk_mul_f32 v[28:29], v[28:29], v[28:29]
	v_pk_mul_f32 v[30:31], v[30:31], v[30:31]
	v_pk_mul_f32 v[26:27], v[26:27], v[26:27]
	v_pk_mul_f32 v[34:35], v[34:35], v[34:35]
	v_pk_mul_f32 v[38:39], v[38:39], v[38:39]
	v_pk_mul_f32 v[36:37], s[6:7], v[36:37] op_sel_hi:[0,1]
	v_pk_mul_f32 v[32:33], s[6:7], v[32:33] op_sel_hi:[0,1]
	v_pk_mul_f32 v[24:25], v[24:25], v[24:25]
	v_pk_mul_f32 v[28:29], s[6:7], v[28:29] op_sel_hi:[0,1]
	v_pk_mul_f32 v[26:27], s[6:7], v[26:27] op_sel_hi:[0,1]
	v_pk_mul_f32 v[30:31], s[6:7], v[30:31] op_sel_hi:[0,1]
	v_pk_mul_f32 v[38:39], s[6:7], v[38:39] op_sel_hi:[0,1]
	v_pk_mul_f32 v[34:35], s[6:7], v[34:35] op_sel_hi:[0,1]
	v_cvt_pk_bf16_f32 v0, v32, v33
	v_cvt_pk_bf16_f32 v3, v36, v37
	v_cvt_pk_bf16_f32 v32, v34, v35
	v_cvt_pk_bf16_f32 v33, v38, v39
	v_pk_mul_f32 v[24:25], s[6:7], v[24:25] op_sel_hi:[0,1]
	v_cvt_pk_bf16_f32 v28, v28, v29
	v_cvt_pk_bf16_f32 v29, v24, v25
	v_cvt_pk_bf16_f32 v30, v30, v31
	v_cvt_pk_bf16_f32 v31, v26, v27
	v_mov_b32_e32 v36, v1
	v_cndmask_b32_e32 v26, v32, v30, vcc
	v_cndmask_b32_e32 v24, v33, v31, vcc
	v_mov_b32_e32 v37, v1
	v_mov_b32_dpp v36, v26 row_ror:8 row_mask:0xf bank_mask:0xf
	v_cndmask_b32_e32 v27, v0, v28, vcc
	v_mov_b32_e32 v34, v1
	v_mov_b32_dpp v37, v24 row_ror:8 row_mask:0xf bank_mask:0xf
	v_cndmask_b32_e32 v26, v36, v32, vcc
	v_add_u32_e32 v32, 0x98, v2
	v_cndmask_b32_e32 v25, v3, v29, vcc
	v_mov_b32_dpp v34, v27 row_ror:8 row_mask:0xf bank_mask:0xf
	v_mov_b32_e32 v35, v1
	v_cndmask_b32_e32 v27, v37, v33, vcc
	v_ashrrev_i32_e32 v33, 31, v32
	s_mov_b32 s0, 0x120000
	v_mov_b32_dpp v35, v25 row_ror:8 row_mask:0xf bank_mask:0xf
	v_cndmask_b32_e32 v24, v34, v0, vcc
	v_cndmask_b32_e32 v28, v28, v34, vcc
	v_lshlrev_b64 v[32:33], 13, v[32:33]
	v_add_co_u32_e64 v34, s[4:5], s0, v14
	v_pk_fma_f32 v[16:17], v[134:135], v[76:77], v[16:17] op_sel_hi:[0,1,1] neg_lo:[1,0,0] neg_hi:[1,0,0]
	v_cndmask_b32_e32 v25, v35, v3, vcc
	v_cndmask_b32_e32 v29, v29, v35, vcc
	v_lshl_add_u64 v[32:33], s[84:85], 0, v[32:33]
	v_addc_co_u32_e64 v35, s[4:5], 0, v15, s[4:5]
	v_pk_fma_f32 v[16:17], v[136:137], v[16:17], v[80:81] op_sel_hi:[0,1,1]
	v_cndmask_b32_e32 v31, v31, v37, vcc
	v_cndmask_b32_e32 v30, v30, v36, vcc
	v_lshl_add_u64 v[32:33], v[32:33], 0, v[12:13]
	global_store_dwordx4 v[34:35], v[24:27], off nt
	global_store_dwordx4 v[32:33], v[28:31], off nt
	v_max_f32_e32 v20, 0, v20
	v_max_f32_e32 v24, 0, v94
	v_max_f32_e32 v25, 0, v95
	v_max_f32_e32 v28, 0, v90
	v_max_f32_e32 v29, 0, v91
	v_max_f32_e32 v22, 0, v22
	v_max_f32_e32 v21, 0, v21
	v_max_f32_e32 v23, 0, v23
	v_max_f32_e32 v18, 0, v18
	v_max_f32_e32 v19, 0, v19
	v_max_f32_e32 v26, 0, v96
	v_max_f32_e32 v27, 0, v97
	v_max_f32_e32 v30, 0, v92
	v_max_f32_e32 v31, 0, v93
	v_pk_mul_f32 v[24:25], v[24:25], v[24:25]
	v_pk_mul_f32 v[28:29], v[28:29], v[28:29]
	v_max_f32_e32 v16, 0, v16
	v_max_f32_e32 v17, 0, v17
	v_pk_mul_f32 v[20:21], v[20:21], v[20:21]
	v_pk_mul_f32 v[22:23], v[22:23], v[22:23]
	v_pk_mul_f32 v[18:19], v[18:19], v[18:19]
	v_pk_mul_f32 v[26:27], v[26:27], v[26:27]
	v_pk_mul_f32 v[30:31], v[30:31], v[30:31]
	v_pk_mul_f32 v[28:29], s[6:7], v[28:29] op_sel_hi:[0,1]
	v_pk_mul_f32 v[24:25], s[6:7], v[24:25] op_sel_hi:[0,1]
	v_pk_mul_f32 v[16:17], v[16:17], v[16:17]
; #define PG8_BAR __builtin_amdgcn_s_barrier()
; template <class Epi, class Sched, bool ALIGN_EPI = false, bool SP2 = false>
; __device__ __forceinline__ void gemm_phase(PG8_LAS unsigned char* lds, const Gemm g, const Sched& S, const Epi& E, const int tid_in) {
;     ...
;         if constexpr (ALIGN_EPI) { if (wr == 0) PG8_BAR; }
;         if constexpr (!Epi::AFTER_DRAIN) { E(acc, cur, wr, wc, fr, fq); S.done(cur); }
;         if (!has_next) break;
; #pragma unroll
;         for (int a = 0; a < 2; ++a)
; #pragma unroll
;             for (int b = 0; b < 2; ++b)
; #pragma unroll
;                 for (int m = 0; m < 4; ++m)
; #pragma unroll
;                     for (int n = 0; n < 2; ++n) acc[a][b][m][n] = (f32x4){0.f, 0.f, 0.f, 0.f};
;         cur = nxt; cA = nA; cB = nB; ++ui;
;         if constexpr (ALIGN_EPI) { if (wr == 1) PG8_BAR; }
;     }
;     __device__ __forceinline__ void operator()(f32x4 (&acc)[2][2][4][2], const Unit& u, int wr, int wc, int fr, int fq) const {
;     ...
;                 for (int bj = 0; bj < 2; ++bj) { f32x4 v0 = acc[ai][bj][m][0], v1 = acc[ai][bj][m][1];
;                     if (act == 1) {
; #pragma unroll
;                         for (int e = 0; e < 4; ++e) { float a = fmaxf(v0[e], 0.f), b = fmaxf(v1[e], 0.f); v0[e] = a * a; v1[e] = b * b; } }
;                     v0 = v0 * sc; v1 = v1 * sc; w[bj].x = cvt_pk_bf16(v0[0], v0[1]); w[bj].y = cvt_pk_bf16(v0[2], v0[3]); w[bj].z = cvt_pk_bf16(v1[0], v1[1]); w[bj].w = cvt_pk_bf16(v1[2], v1[3]); }
;                 const u32x4 snd = hi ? w[0] : w[1]; u32x4 rcv;
;                 rcv.x = (unsigned)__builtin_amdgcn_update_dpp(0, (int)snd.x, 0x128, 0xF, 0xF, false); rcv.y = (unsigned)__builtin_amdgcn_update_dpp(0, (int)snd.y, 0x128, 0xF, 0xF, false);
;                 rcv.z = (unsigned)__builtin_amdgcn_update_dpp(0, (int)snd.z, 0x128, 0xF, 0xF, false); rcv.w = (unsigned)__builtin_amdgcn_update_dpp(0, (int)snd.w, 0x128, 0xF, 0xF, false);
;                 const u32x4 o1 = hi ? rcv : w[0], o2 = hi ? w[1] : rcv;
;                 const int r1 = rbase + ai * HALF + m * 16;
;                 bf16_t* p1 = O + (size_t)(r1 & rowmask) * ldc + colA; bf16_t* p2 = O + (size_t)((r1 + 8) & rowmask) * ldc + colA;
;                 if (O) { *(u32x4*)p1 = o1; *(u32x4*)p2 = o2; } else asm volatile("" :: "v"(o1), "v"(o2));
	v_pk_mul_f32 v[20:21], s[6:7], v[20:21] op_sel_hi:[0,1]
	v_pk_mul_f32 v[18:19], s[6:7], v[18:19] op_sel_hi:[0,1]
	v_pk_mul_f32 v[22:23], s[6:7], v[22:23] op_sel_hi:[0,1]
	v_pk_mul_f32 v[30:31], s[6:7], v[30:31] op_sel_hi:[0,1]
	v_pk_mul_f32 v[26:27], s[6:7], v[26:27] op_sel_hi:[0,1]
	v_cvt_pk_bf16_f32 v0, v24, v25
	v_cvt_pk_bf16_f32 v3, v28, v29
	v_cvt_pk_bf16_f32 v24, v26, v27
	v_cvt_pk_bf16_f32 v25, v30, v31
	v_pk_mul_f32 v[16:17], s[6:7], v[16:17] op_sel_hi:[0,1]
	v_cvt_pk_bf16_f32 v20, v20, v21
	v_cvt_pk_bf16_f32 v21, v16, v17
	v_cvt_pk_bf16_f32 v22, v22, v23
	v_cvt_pk_bf16_f32 v23, v18, v19
	v_mov_b32_e32 v28, v1
	v_cndmask_b32_e32 v18, v24, v22, vcc
	v_cndmask_b32_e32 v16, v25, v23, vcc
	v_mov_b32_e32 v29, v1
	v_mov_b32_dpp v28, v18 row_ror:8 row_mask:0xf bank_mask:0xf
	v_cndmask_b32_e32 v19, v0, v20, vcc
	v_mov_b32_e32 v26, v1
	v_mov_b32_dpp v29, v16 row_ror:8 row_mask:0xf bank_mask:0xf
	v_cndmask_b32_e32 v18, v28, v24, vcc
	v_add_u32_e32 v24, 0xa8, v2
	v_cndmask_b32_e32 v17, v3, v21, vcc
	v_mov_b32_dpp v26, v19 row_ror:8 row_mask:0xf bank_mask:0xf
	v_mov_b32_e32 v27, v1
	v_cndmask_b32_e32 v19, v29, v25, vcc
	v_ashrrev_i32_e32 v25, 31, v24
	s_mov_b32 s0, 0x140000
	v_mov_b32_dpp v27, v17 row_ror:8 row_mask:0xf bank_mask:0xf
	v_cndmask_b32_e32 v16, v26, v0, vcc
	v_cndmask_b32_e32 v20, v20, v26, vcc
	v_lshlrev_b64 v[24:25], 13, v[24:25]
	v_add_co_u32_e64 v26, s[4:5], s0, v14
	v_cndmask_b32_e32 v17, v27, v3, vcc
	v_cndmask_b32_e32 v21, v21, v27, vcc
	v_lshl_add_u64 v[24:25], s[84:85], 0, v[24:25]
	v_addc_co_u32_e64 v27, s[4:5], 0, v15, s[4:5]
	v_cndmask_b32_e32 v23, v23, v29, vcc
	v_cndmask_b32_e32 v22, v22, v28, vcc
	v_lshl_add_u64 v[24:25], v[24:25], 0, v[12:13]
	global_store_dwordx4 v[26:27], v[16:19], off nt
	global_store_dwordx4 v[24:25], v[20:23], off nt
	v_max_f32_e32 v8, 0, v8
	v_max_f32_e32 v16, 0, v86
	v_max_f32_e32 v18, 0, v88
	v_max_f32_e32 v17, 0, v87
	v_max_f32_e32 v19, 0, v89
	v_max_f32_e32 v10, 0, v10
	v_max_f32_e32 v9, 0, v9
	v_max_f32_e32 v11, 0, v11
	v_max_f32_e32 v4, 0, v4
	v_max_f32_e32 v5, 0, v5
	v_max_f32_e32 v20, 0, v82
	v_max_f32_e32 v22, 0, v84
	v_max_f32_e32 v21, 0, v83
	v_max_f32_e32 v23, 0, v85
	v_pk_mul_f32 v[16:17], v[16:17], v[16:17]
	v_pk_mul_f32 v[18:19], v[18:19], v[18:19]
	v_max_f32_e32 v6, 0, v6
	v_max_f32_e32 v7, 0, v7
	v_pk_mul_f32 v[8:9], v[8:9], v[8:9]
	v_pk_mul_f32 v[10:11], v[10:11], v[10:11]
	v_pk_mul_f32 v[4:5], v[4:5], v[4:5]
	v_pk_mul_f32 v[20:21], v[20:21], v[20:21]
	v_pk_mul_f32 v[22:23], v[22:23], v[22:23]
	v_pk_mul_f32 v[16:17], s[6:7], v[16:17] op_sel_hi:[0,1]
	v_pk_mul_f32 v[18:19], s[6:7], v[18:19] op_sel_hi:[0,1]
	v_pk_mul_f32 v[6:7], v[6:7], v[6:7]
	v_pk_mul_f32 v[8:9], s[6:7], v[8:9] op_sel_hi:[0,1]
	v_pk_mul_f32 v[4:5], s[6:7], v[4:5] op_sel_hi:[0,1]
	v_pk_mul_f32 v[10:11], s[6:7], v[10:11] op_sel_hi:[0,1]
	v_pk_mul_f32 v[20:21], s[6:7], v[20:21] op_sel_hi:[0,1]
	v_pk_mul_f32 v[22:23], s[6:7], v[22:23] op_sel_hi:[0,1]
	v_cvt_pk_bf16_f32 v0, v16, v17
	v_cvt_pk_bf16_f32 v3, v20, v21
	v_cvt_pk_bf16_f32 v16, v18, v19
	v_cvt_pk_bf16_f32 v17, v22, v23
	v_pk_mul_f32 v[6:7], s[6:7], v[6:7] op_sel_hi:[0,1]
	v_cvt_pk_bf16_f32 v8, v8, v9
	v_cvt_pk_bf16_f32 v9, v6, v7
	v_cvt_pk_bf16_f32 v10, v10, v11
	v_cvt_pk_bf16_f32 v11, v4, v5
	v_mov_b32_e32 v19, v1
	v_cndmask_b32_e32 v5, v3, v9, vcc
	v_add_u32_e32 v2, 0xb8, v2
	v_cndmask_b32_e32 v4, v17, v11, vcc
	v_mov_b32_dpp v19, v5 row_ror:8 row_mask:0xf bank_mask:0xf
	v_cndmask_b32_e32 v5, v19, v3, vcc
	v_ashrrev_i32_e32 v3, 31, v2
	v_cndmask_b32_e32 v6, v16, v10, vcc
	v_cndmask_b32_e32 v7, v0, v8, vcc
	v_mov_b32_e32 v18, v1
	v_mov_b32_e32 v20, v1
	v_mov_b32_e32 v21, v1
	v_lshlrev_b64 v[2:3], 13, v[2:3]
	v_mov_b32_dpp v18, v7 row_ror:8 row_mask:0xf bank_mask:0xf
	v_mov_b32_dpp v20, v6 row_ror:8 row_mask:0xf bank_mask:0xf
	v_mov_b32_dpp v21, v4 row_ror:8 row_mask:0xf bank_mask:0xf
	v_lshl_add_u64 v[2:3], s[84:85], 0, v[2:3]
	v_cndmask_b32_e32 v7, v21, v17, vcc
	v_cndmask_b32_e32 v4, v18, v0, vcc
	v_cndmask_b32_e32 v6, v20, v16, vcc
	v_cndmask_b32_e32 v9, v9, v19, vcc
	v_cndmask_b32_e32 v11, v11, v21, vcc
	v_cndmask_b32_e32 v8, v8, v18, vcc
	v_cndmask_b32_e32 v10, v10, v20, vcc
	v_lshl_add_u64 v[2:3], v[2:3], 0, v[12:13]
	v_add_co_u32_e32 v12, vcc, 0x160000, v14
	s_mov_b64 s[4:5], -1
	s_nop 0
	v_addc_co_u32_e32 v13, vcc, 0, v15, vcc
	s_andn2_b64 vcc, exec, s[2:3]
	global_store_dwordx4 v[12:13], v[4:7], off nt
	global_store_dwordx4 v[2:3], v[8:11], off nt
	s_cbranch_vccnz .LBB0_650
	s_andn2_b64 vcc, exec, s[18:19]
	s_cbranch_vccnz .LBB0_649
	s_barrier
	s_branch .LBB0_649
